# prologue: non-temporal hint on the read-once weight and activation input loads (on the full bundle)
# speedup vs baseline: 1.0218x; 1.0108x over previous
.LBB0_10:
	s_mul_hi_i32 s2, s59, 0x67b23a55
	s_lshr_b32 s6, s2, 31
	s_ashr_i32 s2, s2, 12
	s_add_i32 s52, s2, s6
	s_mul_i32 s2, s52, 0xffffd880
	s_add_i32 s95, s59, s2
	s_ashr_i32 s53, s52, 31
	v_mad_i64_i32 v[10:11], s[6:7], s52, v20, v[6:7]
	s_cmpk_gt_i32 s95, 0x57f
	s_mov_b64 s[6:7], -1
	s_cbranch_scc0 .LBB0_292
	s_cmpk_gt_u32 s95, 0xaff
	s_cbranch_scc0 .LBB0_225
	s_cmpk_gt_u32 s95, 0x107f
	s_cbranch_scc0 .LBB0_222
	s_cmpk_gt_u32 s95, 0x15ff
	s_cbranch_scc0 .LBB0_155
	s_cmpk_gt_u32 s95, 0x1b7f
	s_cbranch_scc0 .LBB0_88
	s_cmpk_gt_u32 s95, 0x20ff
	s_cbranch_scc0 .LBB0_85
	s_cmpk_gt_u32 s95, 0x257f
	s_cbranch_scc0 .LBB0_18
	s_lshl_b64 s[6:7], s[52:53], 22
	s_add_u32 s54, s36, s6
	s_mul_i32 s2, s52, 0xffffb100
	s_addc_u32 s55, s37, s7
	s_add_i32 s2, s64, s2
	s_addk_i32 s2, 0xcb00
	s_and_b32 s6, s2, 0x1ffc0
	v_or_b32_e32 v9, s6, v3
	s_and_b32 s2, s62, 0x3e0
	v_lshlrev_b32_e32 v12, 12, v9
	v_mov_b32_e32 v13, v5
	v_lshl_add_u64 v[12:13], s[54:55], 0, v[12:13]
	s_lshl_b32 s46, s2, 2
	v_lshl_add_u64 v[12:13], v[12:13], 0, s[46:47]
	v_lshl_add_u64 v[12:13], v[12:13], 0, v[4:5]
	v_add_co_u32_e32 v28, vcc, s75, v12
	s_movk_i32 s7, 0x6000
	s_nop 0
	v_addc_co_u32_e32 v29, vcc, 0, v13, vcc
	v_add_co_u32_e32 v30, vcc, s67, v12
	s_lshl_b32 s46, s6, 1
	s_nop 0
	v_addc_co_u32_e32 v31, vcc, 0, v13, vcc
	v_add_co_u32_e32 v32, vcc, s7, v12
	s_mov_b32 s7, 0x8000
	s_nop 0
	v_addc_co_u32_e32 v33, vcc, 0, v13, vcc
	v_add_co_u32_e32 v34, vcc, s7, v12
	s_mov_b32 s7, 0xa000
	s_nop 0
	v_addc_co_u32_e32 v35, vcc, 0, v13, vcc
	v_add_co_u32_e32 v36, vcc, s7, v12
	s_mov_b32 s7, 0xc000
	s_nop 0
	v_addc_co_u32_e32 v37, vcc, 0, v13, vcc
	v_add_co_u32_e32 v38, vcc, s7, v12
	s_mov_b32 s7, 0xe000
	s_nop 0
	v_addc_co_u32_e32 v39, vcc, 0, v13, vcc
	v_add_co_u32_e32 v40, vcc, s7, v12
	s_mov_b32 s7, 0x14000
	s_nop 0
	v_addc_co_u32_e32 v41, vcc, 0, v13, vcc
	global_load_dword v9, v[12:13], off nt
	global_load_dword v44, v[28:29], off nt
	global_load_dword v45, v[30:31], off nt
	global_load_dword v46, v[32:33], off nt
	global_load_dword v47, v[34:35], off nt
	global_load_dword v48, v[36:37], off nt
	global_load_dword v49, v[38:39], off nt
	global_load_dword v50, v[40:41], off nt
	v_add_co_u32_e32 v28, vcc, s73, v12
	s_nop 1
	v_addc_co_u32_e32 v29, vcc, 0, v13, vcc
	v_add_co_u32_e32 v30, vcc, s76, v12
	s_nop 1
	v_addc_co_u32_e32 v31, vcc, 0, v13, vcc
	v_add_co_u32_e32 v32, vcc, s7, v12
	s_mov_b32 s7, 0x18000
	s_nop 0
	v_addc_co_u32_e32 v33, vcc, 0, v13, vcc
	v_add_co_u32_e32 v34, vcc, s78, v12
	s_nop 1
	v_addc_co_u32_e32 v35, vcc, 0, v13, vcc
	v_add_co_u32_e32 v36, vcc, s7, v12
	s_mov_b32 s7, 0x1a000
	s_nop 0
	v_addc_co_u32_e32 v37, vcc, 0, v13, vcc
	v_add_co_u32_e32 v38, vcc, s7, v12
	s_mov_b32 s7, 0x1c000
	s_nop 0
	v_addc_co_u32_e32 v39, vcc, 0, v13, vcc
	v_add_co_u32_e32 v40, vcc, s7, v12
	s_mov_b32 s7, 0x1e000
	s_nop 0
	v_addc_co_u32_e32 v41, vcc, 0, v13, vcc
	v_add_co_u32_e32 v42, vcc, s7, v12
	s_mov_b32 s7, 0x20000
	s_nop 0
	v_addc_co_u32_e32 v43, vcc, 0, v13, vcc
	global_load_dword v51, v[28:29], off nt
	global_load_dword v52, v[30:31], off nt
	global_load_dword v53, v[32:33], off nt
	global_load_dword v54, v[34:35], off nt
	global_load_dword v55, v[36:37], off nt
	global_load_dword v57, v[38:39], off nt
	global_load_dword v58, v[40:41], off nt
	global_load_dword v59, v[42:43], off nt
	v_add_co_u32_e32 v28, vcc, s7, v12
	s_mov_b32 s7, 0x22000
	s_nop 0
	v_addc_co_u32_e32 v29, vcc, 0, v13, vcc
	v_add_co_u32_e32 v30, vcc, s7, v12
	s_mov_b32 s7, 0x2a000
	s_nop 0
	v_addc_co_u32_e32 v31, vcc, 0, v13, vcc
	v_add_co_u32_e32 v32, vcc, s85, v12
	s_nop 1
	v_addc_co_u32_e32 v33, vcc, 0, v13, vcc
	v_add_co_u32_e32 v34, vcc, s86, v12
	s_nop 1
	v_addc_co_u32_e32 v35, vcc, 0, v13, vcc
	v_add_co_u32_e32 v36, vcc, s87, v12
	s_nop 1
	v_addc_co_u32_e32 v37, vcc, 0, v13, vcc
	v_add_co_u32_e32 v38, vcc, s7, v12
	s_mov_b32 s7, 0x2e000
	s_nop 0
	v_addc_co_u32_e32 v39, vcc, 0, v13, vcc
	v_add_co_u32_e32 v40, vcc, s89, v12
	s_nop 1
	v_addc_co_u32_e32 v41, vcc, 0, v13, vcc
	v_add_co_u32_e32 v42, vcc, s7, v12
	s_mov_b32 s7, 0x30000
	s_nop 0
	v_addc_co_u32_e32 v43, vcc, 0, v13, vcc
	global_load_dword v60, v[28:29], off nt
	global_load_dword v61, v[30:31], off nt
	global_load_dword v62, v[32:33], off nt
	global_load_dword v63, v[34:35], off nt
	global_load_dword v64, v[36:37], off nt
	global_load_dword v65, v[38:39], off nt
	global_load_dword v66, v[40:41], off nt
	s_nop 0
	global_load_dword v42, v[42:43], off nt
	v_add_co_u32_e32 v28, vcc, s7, v12
	s_mov_b32 s7, 0x32000
	s_nop 0
	v_addc_co_u32_e32 v29, vcc, 0, v13, vcc
	v_add_co_u32_e32 v30, vcc, s7, v12
	s_mov_b32 s7, 0x34000
	s_nop 0
	v_addc_co_u32_e32 v31, vcc, 0, v13, vcc
	v_add_co_u32_e32 v32, vcc, s7, v12
	s_mov_b32 s7, 0x38000
	s_nop 0
	v_addc_co_u32_e32 v33, vcc, 0, v13, vcc
	v_add_co_u32_e32 v34, vcc, s94, v12
	s_nop 1
	v_addc_co_u32_e32 v35, vcc, 0, v13, vcc
	v_add_co_u32_e32 v36, vcc, s7, v12
	s_mov_b64 s[6:7], 0x1500000
	s_nop 0
	v_addc_co_u32_e32 v37, vcc, 0, v13, vcc
	v_add_co_u32_e32 v38, vcc, s96, v12
	s_nop 1
	v_addc_co_u32_e32 v39, vcc, 0, v13, vcc
	v_add_co_u32_e32 v40, vcc, s97, v12
	s_nop 1
	v_addc_co_u32_e32 v41, vcc, 0, v13, vcc
	v_add_co_u32_e32 v12, vcc, s48, v12
	s_nop 1
	v_addc_co_u32_e32 v13, vcc, 0, v13, vcc
	global_load_dword v28, v[28:29], off nt
	s_nop 0
	global_load_dword v29, v[30:31], off nt
	s_nop 0
	global_load_dword v30, v[32:33], off nt
	global_load_dword v31, v[34:35], off nt
	s_nop 0
	global_load_dword v32, v[36:37], off nt
	global_load_dword v33, v[38:39], off nt
	global_load_dword v34, v[40:41], off nt
	s_nop 0
	global_load_dword v12, v[12:13], off nt
	s_waitcnt vmcnt(30)
	ds_write2_b32 v14, v9, v44 offset1:66
	s_waitcnt vmcnt(28)
	ds_write2_b32 v14, v45, v46 offset0:132 offset1:198
	s_waitcnt vmcnt(26)
	ds_write2_b32 v21, v47, v48 offset0:8 offset1:74
	s_waitcnt vmcnt(24)
	ds_write2_b32 v21, v49, v50 offset0:140 offset1:206
	s_waitcnt vmcnt(22)
	ds_write2_b32 v22, v51, v52 offset0:16 offset1:82
	s_waitcnt vmcnt(20)
	ds_write2_b32 v22, v53, v54 offset0:148 offset1:214
	s_waitcnt vmcnt(18)
	ds_write2_b32 v23, v55, v57 offset0:24 offset1:90
	s_waitcnt vmcnt(16)
	ds_write2_b32 v23, v58, v59 offset0:156 offset1:222
	s_waitcnt vmcnt(14)
	ds_write2_b32 v24, v60, v61 offset0:32 offset1:98
	s_waitcnt vmcnt(12)
	ds_write2_b32 v24, v62, v63 offset0:164 offset1:230
	s_waitcnt vmcnt(10)
	ds_write2_b32 v25, v64, v65 offset0:40 offset1:106
	s_waitcnt vmcnt(8)
	ds_write2_b32 v25, v66, v42 offset0:172 offset1:238
	s_waitcnt vmcnt(6)
	ds_write2_b32 v26, v28, v29 offset0:48 offset1:114
	s_waitcnt vmcnt(4)
	ds_write2_b32 v26, v30, v31 offset0:180 offset1:246
	s_waitcnt vmcnt(2)
	ds_write2_b32 v27, v32, v33 offset0:56 offset1:122
	s_waitcnt vmcnt(0)
	ds_write2_b32 v27, v34, v12 offset0:188 offset1:254
	s_waitcnt lgkmcnt(0)
	ds_read2_b32 v[32:33], v16 offset0:33 offset1:41
	ds_read2_b32 v[34:35], v16 offset1:8
	ds_read2_b32 v[36:37], v16 offset0:66 offset1:74
	ds_read2_b32 v[38:39], v16 offset0:99 offset1:107
	ds_read2_b32 v[40:41], v16 offset0:132 offset1:140
	ds_read2_b32 v[42:43], v16 offset0:165 offset1:173
	ds_read2_b32 v[44:45], v16 offset0:198 offset1:206
	ds_read2_b32 v[46:47], v16 offset0:231 offset1:239
	v_lshl_add_u64 v[12:13], v[10:11], 0, s[46:47]
	v_mov_b32_e32 v9, v5
	v_lshl_add_u64 v[12:13], v[12:13], 0, v[8:9]
	v_or_b32_e32 v9, s2, v15
	v_lshl_add_u64 v[12:13], v[12:13], 0, s[6:7]
	v_lshlrev_b32_e32 v48, 11, v9
	v_mov_b32_e32 v49, v5
	s_waitcnt lgkmcnt(6)
	v_cvt_pk_bf16_f32 v28, v34, v32
	s_waitcnt lgkmcnt(4)
	v_cvt_pk_bf16_f32 v29, v36, v38
	s_waitcnt lgkmcnt(2)
	v_cvt_pk_bf16_f32 v30, v40, v42
	s_waitcnt lgkmcnt(0)
	v_cvt_pk_bf16_f32 v31, v44, v46
	v_lshl_add_u64 v[48:49], v[12:13], 0, v[48:49]
	global_store_dwordx4 v[48:49], v[28:31], off
	v_or_b32_e32 v9, s2, v17
	v_lshlrev_b32_e32 v32, 11, v9
	v_cvt_pk_bf16_f32 v28, v35, v33
	v_cvt_pk_bf16_f32 v29, v37, v39
	v_cvt_pk_bf16_f32 v30, v41, v43
	v_cvt_pk_bf16_f32 v31, v45, v47
	ds_read2_b32 v[34:35], v16 offset0:49 offset1:57
	ds_read2_b32 v[36:37], v16 offset0:16 offset1:24
	ds_read2_b32 v[38:39], v16 offset0:82 offset1:90
	ds_read2_b32 v[40:41], v16 offset0:115 offset1:123
	ds_read2_b32 v[42:43], v16 offset0:148 offset1:156
	ds_read2_b32 v[44:45], v16 offset0:181 offset1:189
	ds_read2_b32 v[46:47], v16 offset0:214 offset1:222
	ds_read2_b32 v[48:49], v16 offset0:247 offset1:255
	v_mov_b32_e32 v33, v5
	v_lshl_add_u64 v[32:33], v[12:13], 0, v[32:33]
	v_or_b32_e32 v9, s2, v18
	global_store_dwordx4 v[32:33], v[28:31], off
	v_lshlrev_b32_e32 v32, 11, v9
	v_mov_b32_e32 v33, v5
	s_waitcnt lgkmcnt(6)
	v_cvt_pk_bf16_f32 v28, v36, v34
	s_waitcnt lgkmcnt(4)
	v_cvt_pk_bf16_f32 v29, v38, v40
	s_waitcnt lgkmcnt(2)
	v_cvt_pk_bf16_f32 v30, v42, v44
	s_waitcnt lgkmcnt(0)
	v_cvt_pk_bf16_f32 v31, v46, v48
	v_lshl_add_u64 v[32:33], v[12:13], 0, v[32:33]
	v_or_b32_e32 v9, s2, v19
	global_store_dwordx4 v[32:33], v[28:31], off
	v_lshlrev_b32_e32 v32, 11, v9
	v_mov_b32_e32 v33, v5
	v_cvt_pk_bf16_f32 v28, v37, v35
	v_cvt_pk_bf16_f32 v29, v39, v41
	v_cvt_pk_bf16_f32 v30, v43, v45
	v_cvt_pk_bf16_f32 v31, v47, v49
	v_lshl_add_u64 v[12:13], v[12:13], 0, v[32:33]
	global_store_dwordx4 v[12:13], v[28:31], off
	s_waitcnt lgkmcnt(0)
	s_mov_b64 s[6:7], 0
.LBB0_18:
	s_andn2_b64 vcc, exec, s[6:7]
	s_cbranch_vccnz .LBB0_84
	s_mul_i32 s6, s52, 0x900000
	s_mul_hi_i32 s2, s52, 0x900000
	s_add_u32 s6, s30, s6
	s_addc_u32 s7, s31, s2
	s_lshl_b64 s[54:55], s[52:53], 12
	s_add_u32 s54, s28, s54
	s_addc_u32 s55, s29, s55
	s_add_i32 s2, s95, 0xdf00
	s_and_b32 s46, s2, 0xffff
	s_mul_i32 s46, s46, 0xe38f
	s_lshr_b32 s57, s46, 16
	s_lshr_b32 s46, s46, 22
	s_mulk_i32 s46, 0x48
	s_sub_i32 s56, s2, s46
	s_and_b32 s2, s57, 0xffc0
	v_or_b32_e32 v72, s2, v3
	v_mov_b64_e32 v[12:13], s[6:7]
	s_movk_i32 s6, 0x2400
	v_mad_u64_u32 v[12:13], s[6:7], v72, s6, v[12:13]
	s_lshl_b32 s6, s56, 7
	s_and_b32 s46, s6, 0x3ff80
	v_lshl_add_u64 v[12:13], v[12:13], 0, s[46:47]
	v_lshl_add_u64 v[50:51], v[12:13], 0, v[4:5]
	v_add_co_u32_e32 v12, vcc, s67, v50
	s_mov_b32 s6, 0x9000
	s_nop 0
	v_addc_co_u32_e32 v13, vcc, 0, v51, vcc
	v_add_co_u32_e32 v28, vcc, s6, v50
	s_mov_b32 s6, 0xd000
	s_nop 0
	v_addc_co_u32_e32 v29, vcc, 0, v51, vcc
	v_add_co_u32_e32 v34, vcc, s6, v50
	s_mov_b32 s6, 0x1f000
	s_nop 0
	v_addc_co_u32_e32 v35, vcc, 0, v51, vcc
	v_add_co_u32_e32 v36, vcc, s76, v50
	s_nop 1
	v_addc_co_u32_e32 v37, vcc, 0, v51, vcc
	v_add_co_u32_e32 v38, vcc, s78, v50
	s_nop 1
	v_addc_co_u32_e32 v39, vcc, 0, v51, vcc
	v_add_co_u32_e32 v40, vcc, s49, v50
	s_nop 1
	v_addc_co_u32_e32 v41, vcc, 0, v51, vcc
	v_add_co_u32_e32 v42, vcc, s6, v50
	s_mov_b32 s6, 0x2d000
	s_nop 0
	v_addc_co_u32_e32 v43, vcc, 0, v51, vcc
	global_load_dword v31, v[50:51], off nt
	global_load_dword v32, v[12:13], off offset:2048 nt
	s_nop 0
	global_load_dword v28, v[28:29], off nt
	s_nop 0
	global_load_dword v29, v[34:35], off offset:2048 nt
	global_load_dword v12, v[36:37], off nt
	global_load_dword v13, v[38:39], off offset:2048 nt
	global_load_dword v9, v[40:41], off nt
	global_load_dword v30, v[42:43], off offset:2048 nt
	v_add_co_u32_e32 v34, vcc, s85, v50
	s_nop 1
	v_addc_co_u32_e32 v35, vcc, 0, v51, vcc
	v_add_co_u32_e32 v36, vcc, s87, v50
	s_nop 1
	v_addc_co_u32_e32 v37, vcc, 0, v51, vcc
	v_add_co_u32_e32 v42, vcc, s6, v50
	s_mov_b32 s6, 0x3f000
	s_nop 0
	v_addc_co_u32_e32 v43, vcc, 0, v51, vcc
	v_add_co_u32_e32 v44, vcc, s8, v50
	s_nop 1
	v_addc_co_u32_e32 v45, vcc, 0, v51, vcc
	v_add_co_u32_e32 v46, vcc, s94, v50
	s_nop 1
	v_addc_co_u32_e32 v47, vcc, 0, v51, vcc
	v_add_co_u32_e32 v48, vcc, s96, v50
	s_nop 1
	v_addc_co_u32_e32 v49, vcc, 0, v51, vcc
	v_add_co_u32_e32 v52, vcc, s6, v50
	s_mov_b32 s6, 0x43000
	s_nop 0
	v_addc_co_u32_e32 v53, vcc, 0, v51, vcc
	v_add_co_u32_e32 v54, vcc, s6, v50
	s_mov_b32 s6, 0x48000
	s_nop 0
	v_addc_co_u32_e32 v55, vcc, 0, v51, vcc
	global_load_dword v39, v[34:35], off nt
	global_load_dword v40, v[36:37], off offset:2048 nt
	s_nop 0
	global_load_dword v36, v[42:43], off nt
	global_load_dword v37, v[44:45], off offset:2048 nt
	global_load_dword v34, v[46:47], off nt
	global_load_dword v35, v[48:49], off offset:2048 nt
	global_load_dword v33, v[52:53], off nt
	global_load_dword v38, v[54:55], off offset:2048 nt
	v_add_co_u32_e32 v42, vcc, s6, v50
	s_mov_b32 s6, 0x4c000
	s_nop 0
	v_addc_co_u32_e32 v43, vcc, 0, v51, vcc
	v_add_co_u32_e32 v44, vcc, s6, v50
	s_mov_b32 s6, 0x51000
	s_nop 0
	v_addc_co_u32_e32 v45, vcc, 0, v51, vcc
	v_add_co_u32_e32 v52, vcc, s6, v50
	s_mov_b32 s6, 0x55000
	s_nop 0
	v_addc_co_u32_e32 v53, vcc, 0, v51, vcc
	v_add_co_u32_e32 v54, vcc, s6, v50
	s_mov_b32 s6, 0x5a000
	s_nop 0
	v_addc_co_u32_e32 v55, vcc, 0, v51, vcc
	v_add_co_u32_e32 v58, vcc, s6, v50
	s_mov_b32 s6, 0x5e000
	s_nop 0
	v_addc_co_u32_e32 v59, vcc, 0, v51, vcc
	v_add_co_u32_e32 v60, vcc, s6, v50
	s_mov_b32 s6, 0x67000
	s_nop 0
	v_addc_co_u32_e32 v61, vcc, 0, v51, vcc
	v_add_co_u32_e32 v62, vcc, s9, v50
	s_nop 1
	v_addc_co_u32_e32 v63, vcc, 0, v51, vcc
	v_add_co_u32_e32 v64, vcc, s6, v50
	s_mov_b32 s6, 0x6c000
	s_nop 0
	v_addc_co_u32_e32 v65, vcc, 0, v51, vcc
	global_load_dword v47, v[42:43], off nt
	global_load_dword v48, v[44:45], off offset:2048 nt
	s_nop 0
	global_load_dword v44, v[52:53], off nt
	global_load_dword v45, v[54:55], off offset:2048 nt
	global_load_dword v42, v[58:59], off nt
	global_load_dword v43, v[60:61], off offset:2048 nt
	global_load_dword v41, v[62:63], off nt
	global_load_dword v46, v[64:65], off offset:2048 nt
	v_add_co_u32_e32 v52, vcc, s6, v50
	s_mov_b32 s6, 0x70000
	s_nop 0
	v_addc_co_u32_e32 v53, vcc, 0, v51, vcc
	v_add_co_u32_e32 v58, vcc, s6, v50
	s_mov_b32 s6, 0x75000
	s_nop 0
	v_addc_co_u32_e32 v59, vcc, 0, v51, vcc
	v_add_co_u32_e32 v60, vcc, s6, v50
	s_nop 1
	v_addc_co_u32_e32 v61, vcc, 0, v51, vcc
	v_add_co_u32_e32 v62, vcc, s50, v50
	s_nop 1
	v_addc_co_u32_e32 v63, vcc, 0, v51, vcc
	v_add_co_u32_e32 v64, vcc, s51, v50
	s_nop 1
	v_addc_co_u32_e32 v65, vcc, 0, v51, vcc
	v_add_co_u32_e32 v66, vcc, 0x82000, v50
	s_nop 1
	v_addc_co_u32_e32 v67, vcc, 0, v51, vcc
	v_add_co_u32_e32 v68, vcc, 0x87000, v50
	s_nop 1
	v_addc_co_u32_e32 v69, vcc, 0, v51, vcc
	v_add_co_u32_e32 v70, vcc, 0x8b000, v50
	s_nop 1
	v_addc_co_u32_e32 v71, vcc, 0, v51, vcc
	global_load_dword v55, v[52:53], off nt
	global_load_dword v57, v[58:59], off offset:2048 nt
	s_nop 0
	global_load_dword v53, v[60:61], off nt
	global_load_dword v54, v[62:63], off offset:2048 nt
	global_load_dword v50, v[64:65], off nt
	global_load_dword v51, v[66:67], off offset:2048 nt
	global_load_dword v49, v[68:69], off nt
	global_load_dword v52, v[70:71], off offset:2048 nt
	v_readlane_b32 vcc_lo, v254, 9
	v_readlane_b32 vcc_hi, v254, 10
	v_mov_b32_e32 v58, 1.0
	v_lshlrev_b32_e32 v60, 2, v72
	v_cndmask_b32_e64 v59, 0, 1, vcc
	v_cmp_ne_u32_e64 s[6:7], 1, v59
	s_andn2_b64 vcc, exec, vcc
	v_mov_b32_e32 v59, 1.0
	s_cbranch_vccnz .LBB0_21
	global_load_dword v59, v60, s[54:55] nt
.LBB0_21:
	s_and_b64 vcc, exec, s[6:7]
	s_cbranch_vccnz .LBB0_23
	global_load_dword v58, v60, s[54:55] offset:8 nt
.LBB0_23:
	v_mov_b32_e32 v61, 1.0
	s_and_b64 vcc, exec, s[6:7]
	v_mov_b32_e32 v62, 1.0
	s_cbranch_vccnz .LBB0_25
	global_load_dword v62, v60, s[54:55] offset:16 nt
.LBB0_25:
	s_and_b64 vcc, exec, s[6:7]
	s_cbranch_vccnz .LBB0_27
	global_load_dword v61, v60, s[54:55] offset:24 nt
.LBB0_27:
	v_mov_b32_e32 v63, 1.0
	s_and_b64 vcc, exec, s[6:7]
	v_mov_b32_e32 v64, 1.0
	s_cbranch_vccnz .LBB0_29
	global_load_dword v64, v60, s[54:55] offset:32 nt
.LBB0_29:
	s_and_b64 vcc, exec, s[6:7]
	s_cbranch_vccnz .LBB0_31
	global_load_dword v63, v60, s[54:55] offset:40 nt
.LBB0_31:
	v_mov_b32_e32 v65, 1.0
	s_and_b64 vcc, exec, s[6:7]
	v_mov_b32_e32 v66, 1.0
	s_cbranch_vccnz .LBB0_33
	global_load_dword v66, v60, s[54:55] offset:48 nt
.LBB0_33:
	s_and_b64 vcc, exec, s[6:7]
	s_cbranch_vccnz .LBB0_35
	global_load_dword v65, v60, s[54:55] offset:56 nt
.LBB0_35:
	v_mov_b32_e32 v67, 1.0
	s_and_b64 vcc, exec, s[6:7]
	v_mov_b32_e32 v68, 1.0
	s_cbranch_vccnz .LBB0_37
	global_load_dword v68, v60, s[54:55] offset:64 nt
.LBB0_37:
	s_and_b64 vcc, exec, s[6:7]
	s_cbranch_vccnz .LBB0_39
	global_load_dword v67, v60, s[54:55] offset:72 nt
.LBB0_39:
	v_mov_b32_e32 v69, 1.0
	s_and_b64 vcc, exec, s[6:7]
	v_mov_b32_e32 v70, 1.0
	s_cbranch_vccnz .LBB0_41
	global_load_dword v70, v60, s[54:55] offset:80 nt
.LBB0_41:
	s_and_b64 vcc, exec, s[6:7]
	s_cbranch_vccnz .LBB0_43
	global_load_dword v69, v60, s[54:55] offset:88 nt
.LBB0_43:
	v_mov_b32_e32 v71, 1.0
	s_and_b64 vcc, exec, s[6:7]
	v_mov_b32_e32 v72, 1.0
	s_cbranch_vccnz .LBB0_45
	global_load_dword v72, v60, s[54:55] offset:96 nt
.LBB0_45:
	s_and_b64 vcc, exec, s[6:7]
	s_cbranch_vccnz .LBB0_47
	global_load_dword v71, v60, s[54:55] offset:104 nt
.LBB0_47:
	v_mov_b32_e32 v73, 1.0
	s_and_b64 vcc, exec, s[6:7]
	v_mov_b32_e32 v74, 1.0
	s_cbranch_vccnz .LBB0_49
	global_load_dword v74, v60, s[54:55] offset:112 nt
.LBB0_49:
	s_and_b64 vcc, exec, s[6:7]
	s_cbranch_vccnz .LBB0_51
	global_load_dword v73, v60, s[54:55] offset:120 nt
.LBB0_51:
	v_mov_b32_e32 v75, 1.0
	s_and_b64 vcc, exec, s[6:7]
	v_mov_b32_e32 v76, 1.0
	s_cbranch_vccnz .LBB0_53
	global_load_dword v76, v60, s[54:55] offset:128 nt
.LBB0_53:
	s_and_b64 vcc, exec, s[6:7]
	s_cbranch_vccnz .LBB0_55
	global_load_dword v75, v60, s[54:55] offset:136 nt
.LBB0_55:
	v_mov_b32_e32 v77, 1.0
	s_and_b64 vcc, exec, s[6:7]
	v_mov_b32_e32 v78, 1.0
	s_cbranch_vccnz .LBB0_57
	global_load_dword v78, v60, s[54:55] offset:144 nt
.LBB0_57:
	s_and_b64 vcc, exec, s[6:7]
	s_cbranch_vccnz .LBB0_59
	global_load_dword v77, v60, s[54:55] offset:152 nt
.LBB0_59:
	v_mov_b32_e32 v79, 1.0
	s_and_b64 vcc, exec, s[6:7]
	v_mov_b32_e32 v80, 1.0
	s_cbranch_vccnz .LBB0_61
	global_load_dword v80, v60, s[54:55] offset:160 nt
.LBB0_61:
	s_and_b64 vcc, exec, s[6:7]
	s_cbranch_vccnz .LBB0_63
	global_load_dword v79, v60, s[54:55] offset:168 nt
.LBB0_63:
	v_mov_b32_e32 v81, 1.0
	s_and_b64 vcc, exec, s[6:7]
	v_mov_b32_e32 v82, 1.0
	s_cbranch_vccnz .LBB0_65
	global_load_dword v82, v60, s[54:55] offset:176 nt
.LBB0_65:
	s_and_b64 vcc, exec, s[6:7]
	s_cbranch_vccnz .LBB0_67
	global_load_dword v81, v60, s[54:55] offset:184 nt
.LBB0_67:
	v_mov_b32_e32 v83, 1.0
	s_and_b64 vcc, exec, s[6:7]
	v_mov_b32_e32 v84, 1.0
	s_cbranch_vccnz .LBB0_69
	global_load_dword v84, v60, s[54:55] offset:192 nt
.LBB0_69:
	s_and_b64 vcc, exec, s[6:7]
	s_cbranch_vccnz .LBB0_71
	global_load_dword v83, v60, s[54:55] offset:200 nt
.LBB0_71:
	v_mov_b32_e32 v85, 1.0
	s_and_b64 vcc, exec, s[6:7]
	v_mov_b32_e32 v86, 1.0
	s_cbranch_vccnz .LBB0_73
	global_load_dword v86, v60, s[54:55] offset:208 nt
.LBB0_73:
	s_and_b64 vcc, exec, s[6:7]
	s_cbranch_vccnz .LBB0_75
	global_load_dword v85, v60, s[54:55] offset:216 nt
.LBB0_75:
	v_mov_b32_e32 v87, 1.0
	s_and_b64 vcc, exec, s[6:7]
	v_mov_b32_e32 v88, 1.0
	s_cbranch_vccnz .LBB0_77
	global_load_dword v88, v60, s[54:55] offset:224 nt
.LBB0_77:
	s_and_b64 vcc, exec, s[6:7]
	s_cbranch_vccnz .LBB0_79
	global_load_dword v87, v60, s[54:55] offset:232 nt
.LBB0_79:
	v_mov_b32_e32 v89, 1.0
	s_and_b64 vcc, exec, s[6:7]
	v_mov_b32_e32 v90, 1.0
	s_cbranch_vccnz .LBB0_81
	global_load_dword v90, v60, s[54:55] offset:240 nt
.LBB0_81:
	s_and_b64 vcc, exec, s[6:7]
	s_cbranch_vccnz .LBB0_83
	global_load_dword v89, v60, s[54:55] offset:248 nt

.LBB0_85:
	s_andn2_b64 vcc, exec, s[6:7]
	s_cbranch_vccnz .LBB0_87
	s_load_dwordx2 s[54:55], s[0:1], 0x90
	s_mul_i32 s6, s52, 0xb00000
	s_mul_hi_i32 s2, s52, 0xb00000
	v_mov_b32_e32 v13, v5
	s_movk_i32 s7, 0x6000
	s_waitcnt lgkmcnt(0)
	s_add_u32 s54, s54, s6
	s_addc_u32 s55, s55, s2
	s_mul_i32 s2, s52, 0xffffb100
	s_add_i32 s2, s64, s2
	s_addk_i32 s2, 0xdf00
	s_and_b32 s6, s2, 0x1ffc0
	v_or_b32_e32 v9, s6, v3
	s_and_b32 s2, s62, 0x3e0
	v_lshlrev_b32_e32 v12, 12, v9
	v_lshl_add_u64 v[12:13], s[54:55], 0, v[12:13]
	s_lshl_b32 s46, s2, 2
	v_lshl_add_u64 v[12:13], v[12:13], 0, s[46:47]
	v_lshl_add_u64 v[12:13], v[12:13], 0, v[4:5]
	v_add_co_u32_e32 v28, vcc, s75, v12
	s_lshl_b32 s46, s6, 1
	s_nop 0
	v_addc_co_u32_e32 v29, vcc, 0, v13, vcc
	v_add_co_u32_e32 v30, vcc, s67, v12
	s_nop 1
	v_addc_co_u32_e32 v31, vcc, 0, v13, vcc
	v_add_co_u32_e32 v32, vcc, s7, v12
	s_mov_b32 s7, 0x8000
	s_nop 0
	v_addc_co_u32_e32 v33, vcc, 0, v13, vcc
	v_add_co_u32_e32 v34, vcc, s7, v12
	s_mov_b32 s7, 0xa000
	s_nop 0
	v_addc_co_u32_e32 v35, vcc, 0, v13, vcc
	v_add_co_u32_e32 v36, vcc, s7, v12
	s_mov_b32 s7, 0xc000
	s_nop 0
	v_addc_co_u32_e32 v37, vcc, 0, v13, vcc
	v_add_co_u32_e32 v38, vcc, s7, v12
	s_mov_b32 s7, 0xe000
	s_nop 0
	v_addc_co_u32_e32 v39, vcc, 0, v13, vcc
	v_add_co_u32_e32 v40, vcc, s7, v12
	s_mov_b32 s7, 0x14000
	s_nop 0
	v_addc_co_u32_e32 v41, vcc, 0, v13, vcc
	global_load_dword v9, v[12:13], off nt
	global_load_dword v44, v[28:29], off nt
	global_load_dword v45, v[30:31], off nt
	global_load_dword v46, v[32:33], off nt
	global_load_dword v47, v[34:35], off nt
	global_load_dword v48, v[36:37], off nt
	global_load_dword v49, v[38:39], off nt
	global_load_dword v50, v[40:41], off nt
	v_add_co_u32_e32 v28, vcc, s73, v12
	s_nop 1
	v_addc_co_u32_e32 v29, vcc, 0, v13, vcc
	v_add_co_u32_e32 v30, vcc, s76, v12
	s_nop 1
	v_addc_co_u32_e32 v31, vcc, 0, v13, vcc
	v_add_co_u32_e32 v32, vcc, s7, v12
	s_mov_b32 s7, 0x18000
	s_nop 0
	v_addc_co_u32_e32 v33, vcc, 0, v13, vcc
	v_add_co_u32_e32 v34, vcc, s78, v12
	s_nop 1
	v_addc_co_u32_e32 v35, vcc, 0, v13, vcc
	v_add_co_u32_e32 v36, vcc, s7, v12
	s_mov_b32 s7, 0x1a000
	s_nop 0
	v_addc_co_u32_e32 v37, vcc, 0, v13, vcc
	v_add_co_u32_e32 v38, vcc, s7, v12
	s_mov_b32 s7, 0x1c000
	s_nop 0
	v_addc_co_u32_e32 v39, vcc, 0, v13, vcc
	v_add_co_u32_e32 v40, vcc, s7, v12
	s_mov_b32 s7, 0x1e000
	s_nop 0
	v_addc_co_u32_e32 v41, vcc, 0, v13, vcc
	v_add_co_u32_e32 v42, vcc, s7, v12
	s_mov_b32 s7, 0x20000
	s_nop 0
	v_addc_co_u32_e32 v43, vcc, 0, v13, vcc
	global_load_dword v51, v[28:29], off nt
	global_load_dword v52, v[30:31], off nt
	global_load_dword v53, v[32:33], off nt
	global_load_dword v54, v[34:35], off nt
	global_load_dword v55, v[36:37], off nt
	global_load_dword v57, v[38:39], off nt
	global_load_dword v58, v[40:41], off nt
	global_load_dword v59, v[42:43], off nt
	v_add_co_u32_e32 v28, vcc, s7, v12
	s_mov_b32 s7, 0x22000
	s_nop 0
	v_addc_co_u32_e32 v29, vcc, 0, v13, vcc
	v_add_co_u32_e32 v30, vcc, s7, v12
	s_mov_b32 s7, 0x2a000
	s_nop 0
	v_addc_co_u32_e32 v31, vcc, 0, v13, vcc
	v_add_co_u32_e32 v32, vcc, s85, v12
	s_nop 1
	v_addc_co_u32_e32 v33, vcc, 0, v13, vcc
	v_add_co_u32_e32 v34, vcc, s86, v12
	s_nop 1
	v_addc_co_u32_e32 v35, vcc, 0, v13, vcc
	v_add_co_u32_e32 v36, vcc, s87, v12
	s_nop 1
	v_addc_co_u32_e32 v37, vcc, 0, v13, vcc
	v_add_co_u32_e32 v38, vcc, s7, v12
	s_mov_b32 s7, 0x2e000
	s_nop 0
	v_addc_co_u32_e32 v39, vcc, 0, v13, vcc
	v_add_co_u32_e32 v40, vcc, s89, v12
	s_nop 1
	v_addc_co_u32_e32 v41, vcc, 0, v13, vcc
	v_add_co_u32_e32 v42, vcc, s7, v12
	s_mov_b32 s7, 0x30000
	s_nop 0
	v_addc_co_u32_e32 v43, vcc, 0, v13, vcc
	global_load_dword v60, v[28:29], off nt
	global_load_dword v61, v[30:31], off nt
	global_load_dword v62, v[32:33], off nt
	global_load_dword v63, v[34:35], off nt
	global_load_dword v64, v[36:37], off nt
	global_load_dword v65, v[38:39], off nt
	global_load_dword v66, v[40:41], off nt
	s_nop 0
	global_load_dword v42, v[42:43], off nt
	v_add_co_u32_e32 v28, vcc, s7, v12
	s_mov_b32 s7, 0x32000
	s_nop 0
	v_addc_co_u32_e32 v29, vcc, 0, v13, vcc
	v_add_co_u32_e32 v30, vcc, s7, v12
	s_mov_b32 s7, 0x34000
	s_nop 0
	v_addc_co_u32_e32 v31, vcc, 0, v13, vcc
	v_add_co_u32_e32 v32, vcc, s7, v12
	s_mov_b32 s7, 0x38000
	s_nop 0
	v_addc_co_u32_e32 v33, vcc, 0, v13, vcc
	v_add_co_u32_e32 v34, vcc, s94, v12
	s_nop 1
	v_addc_co_u32_e32 v35, vcc, 0, v13, vcc
	v_add_co_u32_e32 v36, vcc, s7, v12
	s_mov_b64 s[6:7], 0x2200000
	s_nop 0
	v_addc_co_u32_e32 v37, vcc, 0, v13, vcc
	v_add_co_u32_e32 v38, vcc, s96, v12
	s_nop 1
	v_addc_co_u32_e32 v39, vcc, 0, v13, vcc
	v_add_co_u32_e32 v40, vcc, s97, v12
	s_nop 1
	v_addc_co_u32_e32 v41, vcc, 0, v13, vcc
	v_add_co_u32_e32 v12, vcc, s48, v12
	s_nop 1
	v_addc_co_u32_e32 v13, vcc, 0, v13, vcc
	global_load_dword v28, v[28:29], off nt
	s_nop 0
	global_load_dword v29, v[30:31], off nt
	s_nop 0
	global_load_dword v30, v[32:33], off nt
	global_load_dword v31, v[34:35], off nt
	s_nop 0
	global_load_dword v32, v[36:37], off nt
	global_load_dword v33, v[38:39], off nt
	global_load_dword v34, v[40:41], off nt
	s_nop 0
	global_load_dword v12, v[12:13], off nt
	s_waitcnt vmcnt(30)
	ds_write2_b32 v14, v9, v44 offset1:66
	s_waitcnt vmcnt(28)
	ds_write2_b32 v14, v45, v46 offset0:132 offset1:198
	s_waitcnt vmcnt(26)
	ds_write2_b32 v21, v47, v48 offset0:8 offset1:74
	s_waitcnt vmcnt(24)
	ds_write2_b32 v21, v49, v50 offset0:140 offset1:206
	s_waitcnt vmcnt(22)
	ds_write2_b32 v22, v51, v52 offset0:16 offset1:82
	s_waitcnt vmcnt(20)
	ds_write2_b32 v22, v53, v54 offset0:148 offset1:214
	s_waitcnt vmcnt(18)
	ds_write2_b32 v23, v55, v57 offset0:24 offset1:90
	s_waitcnt vmcnt(16)
	ds_write2_b32 v23, v58, v59 offset0:156 offset1:222
	s_waitcnt vmcnt(14)
	ds_write2_b32 v24, v60, v61 offset0:32 offset1:98
	s_waitcnt vmcnt(12)
	ds_write2_b32 v24, v62, v63 offset0:164 offset1:230
	s_waitcnt vmcnt(10)
	ds_write2_b32 v25, v64, v65 offset0:40 offset1:106
	s_waitcnt vmcnt(8)
	ds_write2_b32 v25, v66, v42 offset0:172 offset1:238
	s_waitcnt vmcnt(6)
	ds_write2_b32 v26, v28, v29 offset0:48 offset1:114
	s_waitcnt vmcnt(4)
	ds_write2_b32 v26, v30, v31 offset0:180 offset1:246
	s_waitcnt vmcnt(2)
	ds_write2_b32 v27, v32, v33 offset0:56 offset1:122
	s_waitcnt vmcnt(0)
	ds_write2_b32 v27, v34, v12 offset0:188 offset1:254
	s_waitcnt lgkmcnt(0)
	ds_read2_b32 v[32:33], v16 offset0:33 offset1:41
	ds_read2_b32 v[34:35], v16 offset1:8
	ds_read2_b32 v[36:37], v16 offset0:66 offset1:74
	ds_read2_b32 v[38:39], v16 offset0:99 offset1:107
	ds_read2_b32 v[40:41], v16 offset0:132 offset1:140
	ds_read2_b32 v[42:43], v16 offset0:165 offset1:173
	ds_read2_b32 v[44:45], v16 offset0:198 offset1:206
	ds_read2_b32 v[46:47], v16 offset0:231 offset1:239
	v_lshl_add_u64 v[12:13], v[10:11], 0, s[46:47]
	v_mov_b32_e32 v9, v5
	v_lshl_add_u64 v[12:13], v[12:13], 0, v[8:9]
	v_or_b32_e32 v9, s2, v15
	v_mul_u32_u24_e32 v9, 0xb00, v9
	v_lshl_add_u64 v[12:13], v[12:13], 0, s[6:7]
	v_lshlrev_b32_e32 v48, 1, v9
	v_mov_b32_e32 v49, v5
	s_waitcnt lgkmcnt(6)
	v_cvt_pk_bf16_f32 v28, v34, v32
	s_waitcnt lgkmcnt(4)
	v_cvt_pk_bf16_f32 v29, v36, v38
	s_waitcnt lgkmcnt(2)
	v_cvt_pk_bf16_f32 v30, v40, v42
	s_waitcnt lgkmcnt(0)
	v_cvt_pk_bf16_f32 v31, v44, v46
	v_lshl_add_u64 v[48:49], v[12:13], 0, v[48:49]
	global_store_dwordx4 v[48:49], v[28:31], off
	v_or_b32_e32 v9, s2, v17
	v_mul_u32_u24_e32 v9, 0xb00, v9
	v_cvt_pk_bf16_f32 v28, v35, v33
	v_cvt_pk_bf16_f32 v29, v37, v39
	v_cvt_pk_bf16_f32 v30, v41, v43
	v_cvt_pk_bf16_f32 v31, v45, v47
	ds_read2_b32 v[34:35], v16 offset0:16 offset1:24
	ds_read2_b32 v[36:37], v16 offset0:49 offset1:57
	ds_read2_b32 v[38:39], v16 offset0:82 offset1:90
	ds_read2_b32 v[40:41], v16 offset0:115 offset1:123
	ds_read2_b32 v[42:43], v16 offset0:148 offset1:156
	ds_read2_b32 v[44:45], v16 offset0:181 offset1:189
	ds_read2_b32 v[46:47], v16 offset0:214 offset1:222
	ds_read2_b32 v[48:49], v16 offset0:247 offset1:255
	v_lshlrev_b32_e32 v32, 1, v9
	v_mov_b32_e32 v33, v5
	v_or_b32_e32 v9, s2, v18
	v_lshl_add_u64 v[32:33], v[12:13], 0, v[32:33]
	v_mul_u32_u24_e32 v9, 0xb00, v9
	global_store_dwordx4 v[32:33], v[28:31], off
	v_lshlrev_b32_e32 v32, 1, v9
	v_mov_b32_e32 v33, v5
	v_or_b32_e32 v9, s2, v19
	s_waitcnt lgkmcnt(6)
	v_cvt_pk_bf16_f32 v28, v34, v36
	s_waitcnt lgkmcnt(4)
	v_cvt_pk_bf16_f32 v29, v38, v40
	s_waitcnt lgkmcnt(2)
	v_cvt_pk_bf16_f32 v30, v42, v44
	s_waitcnt lgkmcnt(0)
	v_cvt_pk_bf16_f32 v31, v46, v48
	v_lshl_add_u64 v[32:33], v[12:13], 0, v[32:33]
	v_mul_u32_u24_e32 v9, 0xb00, v9
	global_store_dwordx4 v[32:33], v[28:31], off
	v_lshlrev_b32_e32 v32, 1, v9
	v_mov_b32_e32 v33, v5
	v_cvt_pk_bf16_f32 v28, v35, v37
	v_cvt_pk_bf16_f32 v29, v39, v41
	v_cvt_pk_bf16_f32 v30, v43, v45
	v_cvt_pk_bf16_f32 v31, v47, v49
	v_lshl_add_u64 v[12:13], v[12:13], 0, v[32:33]
	global_store_dwordx4 v[12:13], v[28:31], off
	s_waitcnt lgkmcnt(0)

.LBB0_88:
	s_andn2_b64 vcc, exec, s[6:7]
	s_cbranch_vccnz .LBB0_154
	s_mul_i32 s6, s52, 0xb00000
	s_mul_hi_i32 s2, s52, 0xb00000
	s_add_u32 s6, s42, s6
	s_addc_u32 s7, s43, s2
	s_lshl_b64 s[54:55], s[52:53], 12
	s_add_u32 s54, s38, s54
	s_addc_u32 s55, s39, s55
	s_add_i32 s2, s95, 0xea00
	s_and_b32 s46, s2, 0xffff
	s_mul_i32 s46, s46, 0xba2f
	s_lshr_b32 s57, s46, 16
	s_lshr_b32 s46, s46, 22
	s_mulk_i32 s46, 0x58
	s_sub_i32 s2, s2, s46
	s_and_b32 s56, s2, 0xffff
	s_and_b32 s2, s57, 0xffc0
	v_or_b32_e32 v72, s2, v3
	v_mov_b64_e32 v[12:13], s[6:7]
	v_mad_u64_u32 v[12:13], s[6:7], v72, s12, v[12:13]
	s_lshl_b32 s46, s56, 7
	v_lshl_add_u64 v[12:13], v[12:13], 0, s[46:47]
	v_lshl_add_u64 v[50:51], v[12:13], 0, v[4:5]
	v_add_co_u32_e32 v12, vcc, s13, v50
	s_nop 1
	v_addc_co_u32_e32 v13, vcc, 0, v51, vcc
	v_add_co_u32_e32 v28, vcc, s66, v50
	s_nop 1
	v_addc_co_u32_e32 v29, vcc, 0, v51, vcc
	v_add_co_u32_e32 v34, vcc, s73, v50
	s_nop 1
	v_addc_co_u32_e32 v35, vcc, 0, v51, vcc
	v_add_co_u32_e32 v36, vcc, s78, v50
	s_nop 1
	v_addc_co_u32_e32 v37, vcc, 0, v51, vcc
	v_add_co_u32_e32 v38, vcc, s49, v50
	s_nop 1
	v_addc_co_u32_e32 v39, vcc, 0, v51, vcc
	v_add_co_u32_e32 v40, vcc, s68, v50
	s_nop 1
	v_addc_co_u32_e32 v41, vcc, 0, v51, vcc
	v_add_co_u32_e32 v42, vcc, s86, v50
	s_nop 1
	v_addc_co_u32_e32 v43, vcc, 0, v51, vcc
	global_load_dword v31, v[50:51], off nt
	global_load_dword v32, v[12:13], off offset:2048 nt
	s_nop 0
	global_load_dword v28, v[28:29], off nt
	s_nop 0
	global_load_dword v29, v[34:35], off offset:2048 nt
	global_load_dword v12, v[36:37], off nt
	global_load_dword v13, v[38:39], off offset:2048 nt
	global_load_dword v9, v[40:41], off nt
	global_load_dword v30, v[42:43], off offset:2048 nt
	v_add_co_u32_e32 v34, vcc, s89, v50
	s_nop 1
	v_addc_co_u32_e32 v35, vcc, 0, v51, vcc
	v_add_co_u32_e32 v36, vcc, s8, v50
	s_nop 1
	v_addc_co_u32_e32 v37, vcc, 0, v51, vcc
	v_add_co_u32_e32 v42, vcc, s69, v50
	s_nop 1
	v_addc_co_u32_e32 v43, vcc, 0, v51, vcc
	v_add_co_u32_e32 v44, vcc, s97, v50
	s_nop 1
	v_addc_co_u32_e32 v45, vcc, 0, v51, vcc
	v_add_co_u32_e32 v46, vcc, s70, v50
	s_nop 1
	v_addc_co_u32_e32 v47, vcc, 0, v51, vcc
	v_add_co_u32_e32 v48, vcc, s71, v50
	s_nop 1
	v_addc_co_u32_e32 v49, vcc, 0, v51, vcc
	v_add_co_u32_e32 v52, vcc, s72, v50
	s_nop 1
	v_addc_co_u32_e32 v53, vcc, 0, v51, vcc
	v_add_co_u32_e32 v54, vcc, s77, v50
	s_nop 1
	v_addc_co_u32_e32 v55, vcc, 0, v51, vcc
	global_load_dword v39, v[34:35], off nt
	global_load_dword v40, v[36:37], off offset:2048 nt
	s_nop 0
	global_load_dword v36, v[42:43], off nt
	global_load_dword v37, v[44:45], off offset:2048 nt
	global_load_dword v34, v[46:47], off nt
	global_load_dword v35, v[48:49], off offset:2048 nt
	global_load_dword v33, v[52:53], off nt
	global_load_dword v38, v[54:55], off offset:2048 nt
	v_add_co_u32_e32 v42, vcc, s79, v50
	s_nop 1
	v_addc_co_u32_e32 v43, vcc, 0, v51, vcc
	v_add_co_u32_e32 v44, vcc, s80, v50
	s_nop 1
	v_addc_co_u32_e32 v45, vcc, 0, v51, vcc
	v_add_co_u32_e32 v52, vcc, s9, v50
	s_nop 1
	v_addc_co_u32_e32 v53, vcc, 0, v51, vcc
	v_add_co_u32_e32 v54, vcc, s81, v50
	s_nop 1
	v_addc_co_u32_e32 v55, vcc, 0, v51, vcc
	v_add_co_u32_e32 v58, vcc, s82, v50
	s_nop 1
	v_addc_co_u32_e32 v59, vcc, 0, v51, vcc
	v_add_co_u32_e32 v60, vcc, s83, v50
	s_nop 1
	v_addc_co_u32_e32 v61, vcc, 0, v51, vcc
	v_add_co_u32_e32 v62, vcc, s50, v50
	s_nop 1
	v_addc_co_u32_e32 v63, vcc, 0, v51, vcc
	v_add_co_u32_e32 v64, vcc, s51, v50
	s_nop 1
	v_addc_co_u32_e32 v65, vcc, 0, v51, vcc
	global_load_dword v47, v[42:43], off nt
	global_load_dword v48, v[44:45], off offset:2048 nt
	s_nop 0
	global_load_dword v44, v[52:53], off nt
	global_load_dword v45, v[54:55], off offset:2048 nt
	global_load_dword v42, v[58:59], off nt
	global_load_dword v43, v[60:61], off offset:2048 nt
	global_load_dword v41, v[62:63], off nt
	global_load_dword v46, v[64:65], off offset:2048 nt
	v_add_co_u32_e32 v52, vcc, s84, v50
	s_nop 1
	v_addc_co_u32_e32 v53, vcc, 0, v51, vcc
	v_add_co_u32_e32 v58, vcc, s88, v50
	s_nop 1
	v_addc_co_u32_e32 v59, vcc, 0, v51, vcc
	v_add_co_u32_e32 v60, vcc, s90, v50
	s_nop 1
	v_addc_co_u32_e32 v61, vcc, 0, v51, vcc
	v_add_co_u32_e32 v62, vcc, s91, v50
	s_nop 1
	v_addc_co_u32_e32 v63, vcc, 0, v51, vcc
	v_add_co_u32_e32 v64, vcc, s92, v50
	s_nop 1
	v_addc_co_u32_e32 v65, vcc, 0, v51, vcc
	v_add_co_u32_e32 v66, vcc, 0x9f000, v50
	s_nop 1
	v_addc_co_u32_e32 v67, vcc, 0, v51, vcc
	v_add_co_u32_e32 v68, vcc, 0xa5000, v50
	s_nop 1
	v_addc_co_u32_e32 v69, vcc, 0, v51, vcc
	v_add_co_u32_e32 v70, vcc, 0xaa000, v50
	s_nop 1
	v_addc_co_u32_e32 v71, vcc, 0, v51, vcc
	global_load_dword v55, v[52:53], off nt
	global_load_dword v57, v[58:59], off offset:2048 nt
	s_nop 0
	global_load_dword v53, v[60:61], off nt
	global_load_dword v54, v[62:63], off offset:2048 nt
	global_load_dword v50, v[64:65], off nt
	global_load_dword v51, v[66:67], off offset:2048 nt
	global_load_dword v49, v[68:69], off nt
	global_load_dword v52, v[70:71], off offset:2048 nt
	v_cndmask_b32_e64 v59, 0, 1, s[14:15]
	v_mov_b32_e32 v58, 1.0
	v_cmp_ne_u32_e64 s[6:7], 1, v59
	s_andn2_b64 vcc, exec, s[14:15]
	v_lshlrev_b32_e32 v60, 2, v72
	v_mov_b32_e32 v59, 1.0
	s_cbranch_vccnz .LBB0_91
	global_load_dword v59, v60, s[54:55] nt

.LBB0_155:
	s_andn2_b64 vcc, exec, s[6:7]
	s_cbranch_vccnz .LBB0_221
	s_mul_i32 s6, s52, 0xb00000
	s_mul_hi_i32 s2, s52, 0xb00000
	s_add_u32 s6, s40, s6
	s_addc_u32 s7, s41, s2
	s_lshl_b64 s[54:55], s[52:53], 12
	s_add_u32 s54, s38, s54
	s_addc_u32 s55, s39, s55
	s_add_i32 s2, s95, 0xef80
	s_and_b32 s46, s2, 0xffff
	s_mul_i32 s46, s46, 0xba2f
	s_lshr_b32 s57, s46, 16
	s_lshr_b32 s46, s46, 22
	s_mulk_i32 s46, 0x58
	s_sub_i32 s2, s2, s46
	s_and_b32 s56, s2, 0xffff
	s_and_b32 s2, s57, 0xffc0
	v_or_b32_e32 v72, s2, v3
	v_mov_b64_e32 v[12:13], s[6:7]
	v_mad_u64_u32 v[12:13], s[6:7], v72, s12, v[12:13]
	s_lshl_b32 s46, s56, 7
	v_lshl_add_u64 v[12:13], v[12:13], 0, s[46:47]
	v_lshl_add_u64 v[50:51], v[12:13], 0, v[4:5]
	v_add_co_u32_e32 v12, vcc, s13, v50
	s_nop 1
	v_addc_co_u32_e32 v13, vcc, 0, v51, vcc
	v_add_co_u32_e32 v28, vcc, s66, v50
	s_nop 1
	v_addc_co_u32_e32 v29, vcc, 0, v51, vcc
	v_add_co_u32_e32 v34, vcc, s73, v50
	s_nop 1
	v_addc_co_u32_e32 v35, vcc, 0, v51, vcc
	v_add_co_u32_e32 v36, vcc, s78, v50
	s_nop 1
	v_addc_co_u32_e32 v37, vcc, 0, v51, vcc
	v_add_co_u32_e32 v38, vcc, s49, v50
	s_nop 1
	v_addc_co_u32_e32 v39, vcc, 0, v51, vcc
	v_add_co_u32_e32 v40, vcc, s68, v50
	s_nop 1
	v_addc_co_u32_e32 v41, vcc, 0, v51, vcc
	v_add_co_u32_e32 v42, vcc, s86, v50
	s_nop 1
	v_addc_co_u32_e32 v43, vcc, 0, v51, vcc
	global_load_dword v31, v[50:51], off nt
	global_load_dword v32, v[12:13], off offset:2048 nt
	s_nop 0
	global_load_dword v28, v[28:29], off nt
	s_nop 0
	global_load_dword v29, v[34:35], off offset:2048 nt
	global_load_dword v12, v[36:37], off nt
	global_load_dword v13, v[38:39], off offset:2048 nt
	global_load_dword v9, v[40:41], off nt
	global_load_dword v30, v[42:43], off offset:2048 nt
	v_add_co_u32_e32 v34, vcc, s89, v50
	s_nop 1
	v_addc_co_u32_e32 v35, vcc, 0, v51, vcc
	v_add_co_u32_e32 v36, vcc, s8, v50
	s_nop 1
	v_addc_co_u32_e32 v37, vcc, 0, v51, vcc
	v_add_co_u32_e32 v42, vcc, s69, v50
	s_nop 1
	v_addc_co_u32_e32 v43, vcc, 0, v51, vcc
	v_add_co_u32_e32 v44, vcc, s97, v50
	s_nop 1
	v_addc_co_u32_e32 v45, vcc, 0, v51, vcc
	v_add_co_u32_e32 v46, vcc, s70, v50
	s_nop 1
	v_addc_co_u32_e32 v47, vcc, 0, v51, vcc
	v_add_co_u32_e32 v48, vcc, s71, v50
	s_nop 1
	v_addc_co_u32_e32 v49, vcc, 0, v51, vcc
	v_add_co_u32_e32 v52, vcc, s72, v50
	s_nop 1
	v_addc_co_u32_e32 v53, vcc, 0, v51, vcc
	v_add_co_u32_e32 v54, vcc, s77, v50
	s_nop 1
	v_addc_co_u32_e32 v55, vcc, 0, v51, vcc
	global_load_dword v39, v[34:35], off nt
	global_load_dword v40, v[36:37], off offset:2048 nt
	s_nop 0
	global_load_dword v36, v[42:43], off nt
	global_load_dword v37, v[44:45], off offset:2048 nt
	global_load_dword v34, v[46:47], off nt
	global_load_dword v35, v[48:49], off offset:2048 nt
	global_load_dword v33, v[52:53], off nt
	global_load_dword v38, v[54:55], off offset:2048 nt
	v_add_co_u32_e32 v42, vcc, s79, v50
	s_nop 1
	v_addc_co_u32_e32 v43, vcc, 0, v51, vcc
	v_add_co_u32_e32 v44, vcc, s80, v50
	s_nop 1
	v_addc_co_u32_e32 v45, vcc, 0, v51, vcc
	v_add_co_u32_e32 v52, vcc, s9, v50
	s_nop 1
	v_addc_co_u32_e32 v53, vcc, 0, v51, vcc
	v_add_co_u32_e32 v54, vcc, s81, v50
	s_nop 1
	v_addc_co_u32_e32 v55, vcc, 0, v51, vcc
	v_add_co_u32_e32 v58, vcc, s82, v50
	s_nop 1
	v_addc_co_u32_e32 v59, vcc, 0, v51, vcc
	v_add_co_u32_e32 v60, vcc, s83, v50
	s_nop 1
	v_addc_co_u32_e32 v61, vcc, 0, v51, vcc
	v_add_co_u32_e32 v62, vcc, s50, v50
	s_nop 1
	v_addc_co_u32_e32 v63, vcc, 0, v51, vcc
	v_add_co_u32_e32 v64, vcc, s51, v50
	s_nop 1
	v_addc_co_u32_e32 v65, vcc, 0, v51, vcc
	global_load_dword v47, v[42:43], off nt
	global_load_dword v48, v[44:45], off offset:2048 nt
	s_nop 0
	global_load_dword v44, v[52:53], off nt
	global_load_dword v45, v[54:55], off offset:2048 nt
	global_load_dword v42, v[58:59], off nt
	global_load_dword v43, v[60:61], off offset:2048 nt
	global_load_dword v41, v[62:63], off nt
	global_load_dword v46, v[64:65], off offset:2048 nt
	v_add_co_u32_e32 v52, vcc, s84, v50
	s_nop 1
	v_addc_co_u32_e32 v53, vcc, 0, v51, vcc
	v_add_co_u32_e32 v58, vcc, s88, v50
	s_nop 1
	v_addc_co_u32_e32 v59, vcc, 0, v51, vcc
	v_add_co_u32_e32 v60, vcc, s90, v50
	s_nop 1
	v_addc_co_u32_e32 v61, vcc, 0, v51, vcc
	v_add_co_u32_e32 v62, vcc, s91, v50
	s_nop 1
	v_addc_co_u32_e32 v63, vcc, 0, v51, vcc
	v_add_co_u32_e32 v64, vcc, s92, v50
	s_nop 1
	v_addc_co_u32_e32 v65, vcc, 0, v51, vcc
	v_add_co_u32_e32 v66, vcc, 0x9f000, v50
	s_nop 1
	v_addc_co_u32_e32 v67, vcc, 0, v51, vcc
	v_add_co_u32_e32 v68, vcc, 0xa5000, v50
	s_nop 1
	v_addc_co_u32_e32 v69, vcc, 0, v51, vcc
	v_add_co_u32_e32 v70, vcc, 0xaa000, v50
	s_nop 1
	v_addc_co_u32_e32 v71, vcc, 0, v51, vcc
	global_load_dword v55, v[52:53], off nt
	global_load_dword v57, v[58:59], off offset:2048 nt
	s_nop 0
	global_load_dword v53, v[60:61], off nt
	global_load_dword v54, v[62:63], off offset:2048 nt
	global_load_dword v50, v[64:65], off nt
	global_load_dword v51, v[66:67], off offset:2048 nt
	global_load_dword v49, v[68:69], off nt
	global_load_dword v52, v[70:71], off offset:2048 nt
	v_cndmask_b32_e64 v59, 0, 1, s[14:15]
	v_mov_b32_e32 v58, 1.0
	v_cmp_ne_u32_e64 s[6:7], 1, v59
	s_andn2_b64 vcc, exec, s[14:15]
	v_lshlrev_b32_e32 v60, 2, v72
	v_mov_b32_e32 v59, 1.0
	s_cbranch_vccnz .LBB0_158
	global_load_dword v59, v60, s[54:55] nt

.LBB0_222:
	s_andn2_b64 vcc, exec, s[6:7]
	s_cbranch_vccnz .LBB0_224
	s_mul_i32 s6, s52, 0xb00000
	s_mul_hi_i32 s2, s52, 0xb00000
	s_add_u32 s54, s26, s6
	s_addc_u32 s55, s27, s2
	s_mul_i32 s2, s52, 0xffffb100
	s_add_i32 s2, s64, s2
	s_and_b32 s6, s2, 0x1ffc0
	v_or_b32_e32 v9, s6, v3
	s_and_b32 s2, s62, 0x3e0
	v_lshlrev_b32_e32 v12, 12, v9
	v_mov_b32_e32 v13, v5
	v_lshl_add_u64 v[12:13], s[54:55], 0, v[12:13]
	s_lshl_b32 s46, s2, 2
	v_lshl_add_u64 v[12:13], v[12:13], 0, s[46:47]
	v_lshl_add_u64 v[12:13], v[12:13], 0, v[4:5]
	v_add_co_u32_e32 v28, vcc, s75, v12
	s_movk_i32 s7, 0x6000
	s_nop 0
	v_addc_co_u32_e32 v29, vcc, 0, v13, vcc
	v_add_co_u32_e32 v30, vcc, s67, v12
	s_lshl_b32 s46, s6, 1
	s_nop 0
	v_addc_co_u32_e32 v31, vcc, 0, v13, vcc
	v_add_co_u32_e32 v32, vcc, s7, v12
	s_mov_b32 s7, 0x8000
	s_nop 0
	v_addc_co_u32_e32 v33, vcc, 0, v13, vcc
	v_add_co_u32_e32 v34, vcc, s7, v12
	s_mov_b32 s7, 0xa000
	s_nop 0
	v_addc_co_u32_e32 v35, vcc, 0, v13, vcc
	v_add_co_u32_e32 v36, vcc, s7, v12
	s_mov_b32 s7, 0xc000
	s_nop 0
	v_addc_co_u32_e32 v37, vcc, 0, v13, vcc
	v_add_co_u32_e32 v38, vcc, s7, v12
	s_mov_b32 s7, 0xe000
	s_nop 0
	v_addc_co_u32_e32 v39, vcc, 0, v13, vcc
	v_add_co_u32_e32 v40, vcc, s7, v12
	s_mov_b32 s7, 0x14000
	s_nop 0
	v_addc_co_u32_e32 v41, vcc, 0, v13, vcc
	global_load_dword v9, v[12:13], off nt
	global_load_dword v44, v[28:29], off nt
	global_load_dword v45, v[30:31], off nt
	global_load_dword v46, v[32:33], off nt
	global_load_dword v47, v[34:35], off nt
	global_load_dword v48, v[36:37], off nt
	global_load_dword v49, v[38:39], off nt
	global_load_dword v50, v[40:41], off nt
	v_add_co_u32_e32 v28, vcc, s73, v12
	s_nop 1
	v_addc_co_u32_e32 v29, vcc, 0, v13, vcc
	v_add_co_u32_e32 v30, vcc, s76, v12
	s_nop 1
	v_addc_co_u32_e32 v31, vcc, 0, v13, vcc
	v_add_co_u32_e32 v32, vcc, s7, v12
	s_mov_b32 s7, 0x18000
	s_nop 0
	v_addc_co_u32_e32 v33, vcc, 0, v13, vcc
	v_add_co_u32_e32 v34, vcc, s78, v12
	s_nop 1
	v_addc_co_u32_e32 v35, vcc, 0, v13, vcc
	v_add_co_u32_e32 v36, vcc, s7, v12
	s_mov_b32 s7, 0x1a000
	s_nop 0
	v_addc_co_u32_e32 v37, vcc, 0, v13, vcc
	v_add_co_u32_e32 v38, vcc, s7, v12
	s_mov_b32 s7, 0x1c000
	s_nop 0
	v_addc_co_u32_e32 v39, vcc, 0, v13, vcc
	v_add_co_u32_e32 v40, vcc, s7, v12
	s_mov_b32 s7, 0x1e000
	s_nop 0
	v_addc_co_u32_e32 v41, vcc, 0, v13, vcc
	v_add_co_u32_e32 v42, vcc, s7, v12
	s_mov_b32 s7, 0x20000
	s_nop 0
	v_addc_co_u32_e32 v43, vcc, 0, v13, vcc
	global_load_dword v51, v[28:29], off nt
	global_load_dword v52, v[30:31], off nt
	global_load_dword v53, v[32:33], off nt
	global_load_dword v54, v[34:35], off nt
	global_load_dword v55, v[36:37], off nt
	global_load_dword v57, v[38:39], off nt
	global_load_dword v58, v[40:41], off nt
	global_load_dword v59, v[42:43], off nt
	v_add_co_u32_e32 v28, vcc, s7, v12
	s_mov_b32 s7, 0x22000
	s_nop 0
	v_addc_co_u32_e32 v29, vcc, 0, v13, vcc
	v_add_co_u32_e32 v30, vcc, s7, v12
	s_mov_b32 s7, 0x2a000
	s_nop 0
	v_addc_co_u32_e32 v31, vcc, 0, v13, vcc
	v_add_co_u32_e32 v32, vcc, s85, v12
	s_nop 1
	v_addc_co_u32_e32 v33, vcc, 0, v13, vcc
	v_add_co_u32_e32 v34, vcc, s86, v12
	s_nop 1
	v_addc_co_u32_e32 v35, vcc, 0, v13, vcc
	v_add_co_u32_e32 v36, vcc, s87, v12
	s_nop 1
	v_addc_co_u32_e32 v37, vcc, 0, v13, vcc
	v_add_co_u32_e32 v38, vcc, s7, v12
	s_mov_b32 s7, 0x2e000
	s_nop 0
	v_addc_co_u32_e32 v39, vcc, 0, v13, vcc
	v_add_co_u32_e32 v40, vcc, s89, v12
	s_nop 1
	v_addc_co_u32_e32 v41, vcc, 0, v13, vcc
	v_add_co_u32_e32 v42, vcc, s7, v12
	s_mov_b32 s7, 0x30000
	s_nop 0
	v_addc_co_u32_e32 v43, vcc, 0, v13, vcc
	global_load_dword v60, v[28:29], off nt
	global_load_dword v61, v[30:31], off nt
	global_load_dword v62, v[32:33], off nt
	global_load_dword v63, v[34:35], off nt
	global_load_dword v64, v[36:37], off nt
	global_load_dword v65, v[38:39], off nt
	global_load_dword v66, v[40:41], off nt
	s_nop 0
	global_load_dword v42, v[42:43], off nt
	v_add_co_u32_e32 v28, vcc, s7, v12
	s_mov_b32 s7, 0x32000
	s_nop 0
	v_addc_co_u32_e32 v29, vcc, 0, v13, vcc
	v_add_co_u32_e32 v30, vcc, s7, v12
	s_mov_b32 s7, 0x34000
	s_nop 0
	v_addc_co_u32_e32 v31, vcc, 0, v13, vcc
	v_add_co_u32_e32 v32, vcc, s7, v12
	s_mov_b32 s7, 0x38000
	s_nop 0
	v_addc_co_u32_e32 v33, vcc, 0, v13, vcc
	v_add_co_u32_e32 v34, vcc, s94, v12
	s_nop 1
	v_addc_co_u32_e32 v35, vcc, 0, v13, vcc
	v_add_co_u32_e32 v36, vcc, s7, v12
	s_mov_b64 s[6:7], 0xb00000
	s_nop 0
	v_addc_co_u32_e32 v37, vcc, 0, v13, vcc
	v_add_co_u32_e32 v38, vcc, s96, v12
	s_nop 1
	v_addc_co_u32_e32 v39, vcc, 0, v13, vcc
	v_add_co_u32_e32 v40, vcc, s97, v12
	s_nop 1
	v_addc_co_u32_e32 v41, vcc, 0, v13, vcc
	v_add_co_u32_e32 v12, vcc, s48, v12
	s_nop 1
	v_addc_co_u32_e32 v13, vcc, 0, v13, vcc
	global_load_dword v28, v[28:29], off nt
	s_nop 0
	global_load_dword v29, v[30:31], off nt
	s_nop 0
	global_load_dword v30, v[32:33], off nt
	global_load_dword v31, v[34:35], off nt
	s_nop 0
	global_load_dword v32, v[36:37], off nt
	global_load_dword v33, v[38:39], off nt
	global_load_dword v34, v[40:41], off nt
	s_nop 0
	global_load_dword v12, v[12:13], off nt
	s_waitcnt vmcnt(30)
	ds_write2_b32 v14, v9, v44 offset1:66
	s_waitcnt vmcnt(28)
	ds_write2_b32 v14, v45, v46 offset0:132 offset1:198
	s_waitcnt vmcnt(26)
	ds_write2_b32 v21, v47, v48 offset0:8 offset1:74
	s_waitcnt vmcnt(24)
	ds_write2_b32 v21, v49, v50 offset0:140 offset1:206
	s_waitcnt vmcnt(22)
	ds_write2_b32 v22, v51, v52 offset0:16 offset1:82
	s_waitcnt vmcnt(20)
	ds_write2_b32 v22, v53, v54 offset0:148 offset1:214
	s_waitcnt vmcnt(18)
	ds_write2_b32 v23, v55, v57 offset0:24 offset1:90
	s_waitcnt vmcnt(16)
	ds_write2_b32 v23, v58, v59 offset0:156 offset1:222
	s_waitcnt vmcnt(14)
	ds_write2_b32 v24, v60, v61 offset0:32 offset1:98
	s_waitcnt vmcnt(12)
	ds_write2_b32 v24, v62, v63 offset0:164 offset1:230
	s_waitcnt vmcnt(10)
	ds_write2_b32 v25, v64, v65 offset0:40 offset1:106
	s_waitcnt vmcnt(8)
	ds_write2_b32 v25, v66, v42 offset0:172 offset1:238
	s_waitcnt vmcnt(6)
	ds_write2_b32 v26, v28, v29 offset0:48 offset1:114
	s_waitcnt vmcnt(4)
	ds_write2_b32 v26, v30, v31 offset0:180 offset1:246
	s_waitcnt vmcnt(2)
	ds_write2_b32 v27, v32, v33 offset0:56 offset1:122
	s_waitcnt vmcnt(0)
	ds_write2_b32 v27, v34, v12 offset0:188 offset1:254
	s_waitcnt lgkmcnt(0)
	ds_read2_b32 v[32:33], v16 offset0:33 offset1:41
	ds_read2_b32 v[34:35], v16 offset1:8
	ds_read2_b32 v[36:37], v16 offset0:66 offset1:74
	ds_read2_b32 v[38:39], v16 offset0:99 offset1:107
	ds_read2_b32 v[40:41], v16 offset0:132 offset1:140
	ds_read2_b32 v[42:43], v16 offset0:165 offset1:173
	ds_read2_b32 v[44:45], v16 offset0:198 offset1:206
	ds_read2_b32 v[46:47], v16 offset0:231 offset1:239
	v_lshl_add_u64 v[12:13], v[10:11], 0, s[46:47]
	v_mov_b32_e32 v9, v5
	v_lshl_add_u64 v[12:13], v[12:13], 0, v[8:9]
	v_or_b32_e32 v9, s2, v15
	v_mul_u32_u24_e32 v9, 0xb00, v9
	v_lshl_add_u64 v[12:13], v[12:13], 0, s[6:7]
	v_lshlrev_b32_e32 v48, 1, v9
	v_mov_b32_e32 v49, v5
	s_waitcnt lgkmcnt(6)
	v_cvt_pk_bf16_f32 v28, v34, v32
	s_waitcnt lgkmcnt(4)
	v_cvt_pk_bf16_f32 v29, v36, v38
	s_waitcnt lgkmcnt(2)
	v_cvt_pk_bf16_f32 v30, v40, v42
	s_waitcnt lgkmcnt(0)
	v_cvt_pk_bf16_f32 v31, v44, v46
	v_lshl_add_u64 v[48:49], v[12:13], 0, v[48:49]
	global_store_dwordx4 v[48:49], v[28:31], off
	v_or_b32_e32 v9, s2, v17
	v_mul_u32_u24_e32 v9, 0xb00, v9
	v_cvt_pk_bf16_f32 v28, v35, v33
	v_cvt_pk_bf16_f32 v29, v37, v39
	v_cvt_pk_bf16_f32 v30, v41, v43
	v_cvt_pk_bf16_f32 v31, v45, v47
	ds_read2_b32 v[34:35], v16 offset0:16 offset1:24
	ds_read2_b32 v[36:37], v16 offset0:49 offset1:57
	ds_read2_b32 v[38:39], v16 offset0:82 offset1:90
	ds_read2_b32 v[40:41], v16 offset0:115 offset1:123
	ds_read2_b32 v[42:43], v16 offset0:148 offset1:156
	ds_read2_b32 v[44:45], v16 offset0:181 offset1:189
	ds_read2_b32 v[46:47], v16 offset0:214 offset1:222
	ds_read2_b32 v[48:49], v16 offset0:247 offset1:255
	v_lshlrev_b32_e32 v32, 1, v9
	v_mov_b32_e32 v33, v5
	v_or_b32_e32 v9, s2, v18
	v_lshl_add_u64 v[32:33], v[12:13], 0, v[32:33]
	v_mul_u32_u24_e32 v9, 0xb00, v9
	global_store_dwordx4 v[32:33], v[28:31], off
	v_lshlrev_b32_e32 v32, 1, v9
	v_mov_b32_e32 v33, v5
	v_or_b32_e32 v9, s2, v19
	s_waitcnt lgkmcnt(6)
	v_cvt_pk_bf16_f32 v28, v34, v36
	s_waitcnt lgkmcnt(4)
	v_cvt_pk_bf16_f32 v29, v38, v40
	s_waitcnt lgkmcnt(2)
	v_cvt_pk_bf16_f32 v30, v42, v44
	s_waitcnt lgkmcnt(0)
	v_cvt_pk_bf16_f32 v31, v46, v48
	v_lshl_add_u64 v[32:33], v[12:13], 0, v[32:33]
	v_mul_u32_u24_e32 v9, 0xb00, v9
	global_store_dwordx4 v[32:33], v[28:31], off
	v_lshlrev_b32_e32 v32, 1, v9
	v_mov_b32_e32 v33, v5
	v_cvt_pk_bf16_f32 v28, v35, v37
	v_cvt_pk_bf16_f32 v29, v39, v41
	v_cvt_pk_bf16_f32 v30, v43, v45
	v_cvt_pk_bf16_f32 v31, v47, v49
	v_lshl_add_u64 v[12:13], v[12:13], 0, v[32:33]
	global_store_dwordx4 v[12:13], v[28:31], off
	s_waitcnt lgkmcnt(0)

.LBB0_225:
	s_andn2_b64 vcc, exec, s[6:7]
	s_cbranch_vccnz .LBB0_291
	s_mul_i32 s6, s52, 0xb00000
	s_mul_hi_i32 s2, s52, 0xb00000
	s_add_u32 s6, s24, s6
	s_addc_u32 s7, s25, s2
	s_lshl_b64 s[54:55], s[52:53], 12
	s_add_u32 s54, s20, s54
	s_addc_u32 s55, s21, s55
	s_add_i32 s2, s95, 0xfa80
	s_and_b32 s46, s2, 0xffff
	s_mul_i32 s46, s46, 0xba2f
	s_lshr_b32 s57, s46, 16
	s_lshr_b32 s46, s46, 22
	s_mulk_i32 s46, 0x58
	s_sub_i32 s2, s2, s46
	s_and_b32 s56, s2, 0xffff
	s_and_b32 s2, s57, 0xffc0
	v_or_b32_e32 v72, s2, v3
	v_mov_b64_e32 v[12:13], s[6:7]
	v_mad_u64_u32 v[12:13], s[6:7], v72, s12, v[12:13]
	s_lshl_b32 s46, s56, 7
	v_lshl_add_u64 v[12:13], v[12:13], 0, s[46:47]
	v_lshl_add_u64 v[50:51], v[12:13], 0, v[4:5]
	v_add_co_u32_e32 v12, vcc, s13, v50
	s_nop 1
	v_addc_co_u32_e32 v13, vcc, 0, v51, vcc
	v_add_co_u32_e32 v28, vcc, s66, v50
	s_nop 1
	v_addc_co_u32_e32 v29, vcc, 0, v51, vcc
	v_add_co_u32_e32 v34, vcc, s73, v50
	s_nop 1
	v_addc_co_u32_e32 v35, vcc, 0, v51, vcc
	v_add_co_u32_e32 v36, vcc, s78, v50
	s_nop 1
	v_addc_co_u32_e32 v37, vcc, 0, v51, vcc
	v_add_co_u32_e32 v38, vcc, s49, v50
	s_nop 1
	v_addc_co_u32_e32 v39, vcc, 0, v51, vcc
	v_add_co_u32_e32 v40, vcc, s68, v50
	s_nop 1
	v_addc_co_u32_e32 v41, vcc, 0, v51, vcc
	v_add_co_u32_e32 v42, vcc, s86, v50
	s_nop 1
	v_addc_co_u32_e32 v43, vcc, 0, v51, vcc
	global_load_dword v31, v[50:51], off nt
	global_load_dword v32, v[12:13], off offset:2048 nt
	s_nop 0
	global_load_dword v28, v[28:29], off nt
	s_nop 0
	global_load_dword v29, v[34:35], off offset:2048 nt
	global_load_dword v12, v[36:37], off nt
	global_load_dword v13, v[38:39], off offset:2048 nt
	global_load_dword v9, v[40:41], off nt
	global_load_dword v30, v[42:43], off offset:2048 nt
	v_add_co_u32_e32 v34, vcc, s89, v50
	s_nop 1
	v_addc_co_u32_e32 v35, vcc, 0, v51, vcc
	v_add_co_u32_e32 v36, vcc, s8, v50
	s_nop 1
	v_addc_co_u32_e32 v37, vcc, 0, v51, vcc
	v_add_co_u32_e32 v42, vcc, s69, v50
	s_nop 1
	v_addc_co_u32_e32 v43, vcc, 0, v51, vcc
	v_add_co_u32_e32 v44, vcc, s97, v50
	s_nop 1
	v_addc_co_u32_e32 v45, vcc, 0, v51, vcc
	v_add_co_u32_e32 v46, vcc, s70, v50
	s_nop 1
	v_addc_co_u32_e32 v47, vcc, 0, v51, vcc
	v_add_co_u32_e32 v48, vcc, s71, v50
	s_nop 1
	v_addc_co_u32_e32 v49, vcc, 0, v51, vcc
	v_add_co_u32_e32 v52, vcc, s72, v50
	s_nop 1
	v_addc_co_u32_e32 v53, vcc, 0, v51, vcc
	v_add_co_u32_e32 v54, vcc, s77, v50
	s_nop 1
	v_addc_co_u32_e32 v55, vcc, 0, v51, vcc
	global_load_dword v39, v[34:35], off nt
	global_load_dword v40, v[36:37], off offset:2048 nt
	s_nop 0
	global_load_dword v36, v[42:43], off nt
	global_load_dword v37, v[44:45], off offset:2048 nt
	global_load_dword v34, v[46:47], off nt
	global_load_dword v35, v[48:49], off offset:2048 nt
	global_load_dword v33, v[52:53], off nt
	global_load_dword v38, v[54:55], off offset:2048 nt
	v_add_co_u32_e32 v42, vcc, s79, v50
	s_nop 1
	v_addc_co_u32_e32 v43, vcc, 0, v51, vcc
	v_add_co_u32_e32 v44, vcc, s80, v50
	s_nop 1
	v_addc_co_u32_e32 v45, vcc, 0, v51, vcc
	v_add_co_u32_e32 v52, vcc, s9, v50
	s_nop 1
	v_addc_co_u32_e32 v53, vcc, 0, v51, vcc
	v_add_co_u32_e32 v54, vcc, s81, v50
	s_nop 1
	v_addc_co_u32_e32 v55, vcc, 0, v51, vcc
	v_add_co_u32_e32 v58, vcc, s82, v50
	s_nop 1
	v_addc_co_u32_e32 v59, vcc, 0, v51, vcc
	v_add_co_u32_e32 v60, vcc, s83, v50
	s_nop 1
	v_addc_co_u32_e32 v61, vcc, 0, v51, vcc
	v_add_co_u32_e32 v62, vcc, s50, v50
	s_nop 1
	v_addc_co_u32_e32 v63, vcc, 0, v51, vcc
	v_add_co_u32_e32 v64, vcc, s51, v50
	s_nop 1
	v_addc_co_u32_e32 v65, vcc, 0, v51, vcc
	global_load_dword v47, v[42:43], off nt
	global_load_dword v48, v[44:45], off offset:2048 nt
	s_nop 0
	global_load_dword v44, v[52:53], off nt
	global_load_dword v45, v[54:55], off offset:2048 nt
	global_load_dword v42, v[58:59], off nt
	global_load_dword v43, v[60:61], off offset:2048 nt
	global_load_dword v41, v[62:63], off nt
	global_load_dword v46, v[64:65], off offset:2048 nt
	v_add_co_u32_e32 v52, vcc, s84, v50
	s_nop 1
	v_addc_co_u32_e32 v53, vcc, 0, v51, vcc
	v_add_co_u32_e32 v58, vcc, s88, v50
	s_nop 1
	v_addc_co_u32_e32 v59, vcc, 0, v51, vcc
	v_add_co_u32_e32 v60, vcc, s90, v50
	s_nop 1
	v_addc_co_u32_e32 v61, vcc, 0, v51, vcc
	v_add_co_u32_e32 v62, vcc, s91, v50
	s_nop 1
	v_addc_co_u32_e32 v63, vcc, 0, v51, vcc
	v_add_co_u32_e32 v64, vcc, s92, v50
	s_nop 1
	v_addc_co_u32_e32 v65, vcc, 0, v51, vcc
	v_add_co_u32_e32 v66, vcc, 0x9f000, v50
	s_nop 1
	v_addc_co_u32_e32 v67, vcc, 0, v51, vcc
	v_add_co_u32_e32 v68, vcc, 0xa5000, v50
	s_nop 1
	v_addc_co_u32_e32 v69, vcc, 0, v51, vcc
	v_add_co_u32_e32 v70, vcc, 0xaa000, v50
	s_nop 1
	v_addc_co_u32_e32 v71, vcc, 0, v51, vcc
	global_load_dword v55, v[52:53], off nt
	global_load_dword v57, v[58:59], off offset:2048 nt
	s_nop 0
	global_load_dword v53, v[60:61], off nt
	global_load_dword v54, v[62:63], off offset:2048 nt
	global_load_dword v50, v[64:65], off nt
	global_load_dword v51, v[66:67], off offset:2048 nt
	global_load_dword v49, v[68:69], off nt
	global_load_dword v52, v[70:71], off offset:2048 nt
	v_cndmask_b32_e64 v59, 0, 1, s[44:45]
	v_mov_b32_e32 v58, 1.0
	v_cmp_ne_u32_e64 s[6:7], 1, v59
	s_andn2_b64 vcc, exec, s[44:45]
	v_lshlrev_b32_e32 v60, 2, v72
	v_mov_b32_e32 v59, 1.0
	s_cbranch_vccnz .LBB0_228
	global_load_dword v59, v60, s[54:55] nt

.LBB0_292:
	s_andn2_b64 vcc, exec, s[6:7]
	s_cbranch_vccnz .LBB0_9
	s_mul_i32 s6, s52, 0xb00000
	s_mul_hi_i32 s2, s52, 0xb00000
	s_add_u32 s6, s22, s6
	s_addc_u32 s7, s23, s2
	s_lshl_b64 s[52:53], s[52:53], 12
	s_add_u32 s56, s20, s52
	s_mul_i32 s2, s95, 0xba3
	s_addc_u32 s57, s21, s53
	s_lshr_b32 s46, s2, 31
	s_ashr_i32 s2, s2, 18
	s_add_i32 s46, s2, s46
	s_mul_i32 s2, s46, 0x58
	s_sub_i32 s2, s95, s2
	s_lshl_b32 s52, s46, 6
	s_sext_i32_i16 s2, s2
	v_or_b32_e32 v12, s52, v3
	s_lshl_b32 s54, s2, 5
	v_mul_hi_i32_i24_e32 v29, 0x2c00, v12
	v_mul_i32_i24_e32 v28, 0x2c00, v12
	v_lshl_add_u64 v[28:29], s[6:7], 0, v[28:29]
	s_ashr_i32 s55, s54, 31
	v_lshl_add_u64 v[28:29], s[54:55], 2, v[28:29]
	v_lshl_add_u64 v[52:53], v[28:29], 0, v[4:5]
	v_add_co_u32_e32 v28, vcc, s13, v52
	v_ashrrev_i32_e32 v13, 31, v12
	s_nop 0
	v_addc_co_u32_e32 v29, vcc, 0, v53, vcc
	v_add_co_u32_e32 v30, vcc, s66, v52
	v_lshl_add_u64 v[12:13], v[12:13], 2, s[56:57]
	s_nop 0
	v_addc_co_u32_e32 v31, vcc, 0, v53, vcc
	v_add_co_u32_e32 v36, vcc, s73, v52
	s_nop 1
	v_addc_co_u32_e32 v37, vcc, 0, v53, vcc
	v_add_co_u32_e32 v38, vcc, s78, v52
	s_nop 1
	v_addc_co_u32_e32 v39, vcc, 0, v53, vcc
	v_add_co_u32_e32 v40, vcc, s49, v52
	s_nop 1
	v_addc_co_u32_e32 v41, vcc, 0, v53, vcc
	v_add_co_u32_e32 v42, vcc, s68, v52
	s_nop 1
	v_addc_co_u32_e32 v43, vcc, 0, v53, vcc
	v_add_co_u32_e32 v44, vcc, s86, v52
	s_nop 1
	v_addc_co_u32_e32 v45, vcc, 0, v53, vcc
	global_load_dword v33, v[52:53], off nt
	global_load_dword v34, v[28:29], off offset:2048 nt
	s_nop 0
	global_load_dword v30, v[30:31], off nt
	s_nop 0
	global_load_dword v31, v[36:37], off offset:2048 nt
	global_load_dword v28, v[38:39], off nt
	global_load_dword v29, v[40:41], off offset:2048 nt
	global_load_dword v9, v[42:43], off nt
	global_load_dword v32, v[44:45], off offset:2048 nt
	v_add_co_u32_e32 v36, vcc, s89, v52
	s_nop 1
	v_addc_co_u32_e32 v37, vcc, 0, v53, vcc
	v_add_co_u32_e32 v38, vcc, s8, v52
	s_nop 1
	v_addc_co_u32_e32 v39, vcc, 0, v53, vcc
	v_add_co_u32_e32 v44, vcc, s69, v52
	s_nop 1
	v_addc_co_u32_e32 v45, vcc, 0, v53, vcc
	v_add_co_u32_e32 v46, vcc, s97, v52
	s_nop 1
	v_addc_co_u32_e32 v47, vcc, 0, v53, vcc
	v_add_co_u32_e32 v48, vcc, s70, v52
	s_nop 1
	v_addc_co_u32_e32 v49, vcc, 0, v53, vcc
	v_add_co_u32_e32 v50, vcc, s71, v52
	s_nop 1
	v_addc_co_u32_e32 v51, vcc, 0, v53, vcc
	v_add_co_u32_e32 v54, vcc, s72, v52
	s_nop 1
	v_addc_co_u32_e32 v55, vcc, 0, v53, vcc
	v_add_co_u32_e32 v58, vcc, s77, v52
	s_nop 1
	v_addc_co_u32_e32 v59, vcc, 0, v53, vcc
	global_load_dword v41, v[36:37], off nt
	global_load_dword v42, v[38:39], off offset:2048 nt
	s_nop 0
	global_load_dword v38, v[44:45], off nt
	global_load_dword v39, v[46:47], off offset:2048 nt
	global_load_dword v36, v[48:49], off nt
	global_load_dword v37, v[50:51], off offset:2048 nt
	global_load_dword v35, v[54:55], off nt
	global_load_dword v40, v[58:59], off offset:2048 nt
	v_add_co_u32_e32 v44, vcc, s79, v52
	s_nop 1
	v_addc_co_u32_e32 v45, vcc, 0, v53, vcc
	v_add_co_u32_e32 v46, vcc, s80, v52
	s_nop 1
	v_addc_co_u32_e32 v47, vcc, 0, v53, vcc
	v_add_co_u32_e32 v54, vcc, s9, v52
	s_nop 1
	v_addc_co_u32_e32 v55, vcc, 0, v53, vcc
	v_add_co_u32_e32 v58, vcc, s81, v52
	s_nop 1
	v_addc_co_u32_e32 v59, vcc, 0, v53, vcc
	v_add_co_u32_e32 v60, vcc, s82, v52
	s_nop 1
	v_addc_co_u32_e32 v61, vcc, 0, v53, vcc
	v_add_co_u32_e32 v62, vcc, s83, v52
	s_nop 1
	v_addc_co_u32_e32 v63, vcc, 0, v53, vcc
	v_add_co_u32_e32 v64, vcc, s50, v52
	s_nop 1
	v_addc_co_u32_e32 v65, vcc, 0, v53, vcc
	v_add_co_u32_e32 v66, vcc, s51, v52
	s_nop 1
	v_addc_co_u32_e32 v67, vcc, 0, v53, vcc
	global_load_dword v49, v[44:45], off nt
	global_load_dword v50, v[46:47], off offset:2048 nt
	s_nop 0
	global_load_dword v46, v[54:55], off nt
	global_load_dword v47, v[58:59], off offset:2048 nt
	global_load_dword v44, v[60:61], off nt
	global_load_dword v45, v[62:63], off offset:2048 nt
	global_load_dword v43, v[64:65], off nt
	global_load_dword v48, v[66:67], off offset:2048 nt
	v_add_co_u32_e32 v54, vcc, s84, v52
	s_nop 1
	v_addc_co_u32_e32 v55, vcc, 0, v53, vcc
	v_add_co_u32_e32 v60, vcc, s88, v52
	s_nop 1
	v_addc_co_u32_e32 v61, vcc, 0, v53, vcc
	v_add_co_u32_e32 v62, vcc, s90, v52
	s_nop 1
	v_addc_co_u32_e32 v63, vcc, 0, v53, vcc
	v_add_co_u32_e32 v64, vcc, s91, v52
	s_nop 1
	v_addc_co_u32_e32 v65, vcc, 0, v53, vcc
	v_add_co_u32_e32 v66, vcc, s92, v52
	s_nop 1
	v_addc_co_u32_e32 v67, vcc, 0, v53, vcc
	v_add_co_u32_e32 v68, vcc, 0x9f000, v52
	s_nop 1
	v_addc_co_u32_e32 v69, vcc, 0, v53, vcc
	v_add_co_u32_e32 v70, vcc, 0xa5000, v52
	s_nop 1
	v_addc_co_u32_e32 v71, vcc, 0, v53, vcc
	v_add_co_u32_e32 v72, vcc, 0xaa000, v52
	s_nop 1
	v_addc_co_u32_e32 v73, vcc, 0, v53, vcc
	global_load_dword v58, v[54:55], off nt
	global_load_dword v59, v[60:61], off offset:2048 nt
	s_nop 0
	global_load_dword v55, v[62:63], off nt
	global_load_dword v57, v[64:65], off offset:2048 nt
	global_load_dword v52, v[66:67], off nt
	global_load_dword v53, v[68:69], off offset:2048 nt
	global_load_dword v51, v[70:71], off nt
	global_load_dword v54, v[72:73], off offset:2048 nt
	v_cndmask_b32_e64 v61, 0, 1, s[44:45]
	v_mov_b32_e32 v60, 1.0
	v_cmp_ne_u32_e64 s[6:7], 1, v61
	s_andn2_b64 vcc, exec, s[44:45]
	v_mov_b32_e32 v61, 1.0
	s_cbranch_vccnz .LBB0_295
	global_load_dword v61, v[12:13], off nt
.LBB0_295:
	s_and_b64 vcc, exec, s[6:7]
	s_cbranch_vccnz .LBB0_297
	global_load_dword v60, v[12:13], off offset:8 nt
.LBB0_297:
	v_mov_b32_e32 v62, 1.0
	s_and_b64 vcc, exec, s[6:7]
	v_mov_b32_e32 v63, 1.0
	s_cbranch_vccnz .LBB0_299
	global_load_dword v63, v[12:13], off offset:16 nt
.LBB0_299:
	s_and_b64 vcc, exec, s[6:7]
	s_cbranch_vccnz .LBB0_301
	global_load_dword v62, v[12:13], off offset:24 nt
.LBB0_301:
	v_mov_b32_e32 v64, 1.0
	s_and_b64 vcc, exec, s[6:7]
	v_mov_b32_e32 v65, 1.0
	s_cbranch_vccnz .LBB0_303
	global_load_dword v65, v[12:13], off offset:32 nt
.LBB0_303:
	s_and_b64 vcc, exec, s[6:7]
	s_cbranch_vccnz .LBB0_305
	global_load_dword v64, v[12:13], off offset:40 nt
.LBB0_305:
	v_mov_b32_e32 v66, 1.0
	s_and_b64 vcc, exec, s[6:7]
	v_mov_b32_e32 v67, 1.0
	s_cbranch_vccnz .LBB0_307
	global_load_dword v67, v[12:13], off offset:48 nt
.LBB0_307:
	s_and_b64 vcc, exec, s[6:7]
	s_cbranch_vccnz .LBB0_309
	global_load_dword v66, v[12:13], off offset:56 nt
.LBB0_309:
	v_mov_b32_e32 v68, 1.0
	s_and_b64 vcc, exec, s[6:7]
	v_mov_b32_e32 v69, 1.0
	s_cbranch_vccnz .LBB0_311
	global_load_dword v69, v[12:13], off offset:64 nt
.LBB0_311:
	s_and_b64 vcc, exec, s[6:7]
	s_cbranch_vccnz .LBB0_313
	global_load_dword v68, v[12:13], off offset:72 nt
.LBB0_313:
	v_mov_b32_e32 v70, 1.0
	s_and_b64 vcc, exec, s[6:7]
	v_mov_b32_e32 v71, 1.0
	s_cbranch_vccnz .LBB0_315
	global_load_dword v71, v[12:13], off offset:80 nt
.LBB0_315:
	s_and_b64 vcc, exec, s[6:7]
	s_cbranch_vccnz .LBB0_317
	global_load_dword v70, v[12:13], off offset:88 nt
.LBB0_317:
	v_mov_b32_e32 v72, 1.0
	s_and_b64 vcc, exec, s[6:7]
	v_mov_b32_e32 v73, 1.0
	s_cbranch_vccnz .LBB0_319
	global_load_dword v73, v[12:13], off offset:96 nt
.LBB0_319:
	s_and_b64 vcc, exec, s[6:7]
	s_cbranch_vccnz .LBB0_321
	global_load_dword v72, v[12:13], off offset:104 nt
.LBB0_321:
	v_mov_b32_e32 v74, 1.0
	s_and_b64 vcc, exec, s[6:7]
	v_mov_b32_e32 v75, 1.0
	s_cbranch_vccnz .LBB0_323
	global_load_dword v75, v[12:13], off offset:112 nt
.LBB0_323:
	s_and_b64 vcc, exec, s[6:7]
	s_cbranch_vccnz .LBB0_325
	global_load_dword v74, v[12:13], off offset:120 nt
.LBB0_325:
	v_mov_b32_e32 v76, 1.0
	s_and_b64 vcc, exec, s[6:7]
	v_mov_b32_e32 v77, 1.0
	s_cbranch_vccnz .LBB0_327
	global_load_dword v77, v[12:13], off offset:128 nt
.LBB0_327:
	s_and_b64 vcc, exec, s[6:7]
	s_cbranch_vccnz .LBB0_329
	global_load_dword v76, v[12:13], off offset:136 nt
.LBB0_329:
	v_mov_b32_e32 v78, 1.0
	s_and_b64 vcc, exec, s[6:7]
	v_mov_b32_e32 v79, 1.0
	s_cbranch_vccnz .LBB0_331
	global_load_dword v79, v[12:13], off offset:144 nt
.LBB0_331:
	s_and_b64 vcc, exec, s[6:7]
	s_cbranch_vccnz .LBB0_333
	global_load_dword v78, v[12:13], off offset:152 nt
.LBB0_333:
	v_mov_b32_e32 v80, 1.0
	s_and_b64 vcc, exec, s[6:7]
	v_mov_b32_e32 v81, 1.0
	s_cbranch_vccnz .LBB0_335
	global_load_dword v81, v[12:13], off offset:160 nt
.LBB0_335:
	s_and_b64 vcc, exec, s[6:7]
	s_cbranch_vccnz .LBB0_337
	global_load_dword v80, v[12:13], off offset:168 nt
.LBB0_337:
	v_mov_b32_e32 v82, 1.0
	s_and_b64 vcc, exec, s[6:7]
	v_mov_b32_e32 v83, 1.0
	s_cbranch_vccnz .LBB0_339
	global_load_dword v83, v[12:13], off offset:176 nt
.LBB0_339:
	s_and_b64 vcc, exec, s[6:7]
	s_cbranch_vccnz .LBB0_341
	global_load_dword v82, v[12:13], off offset:184 nt
.LBB0_341:
	v_mov_b32_e32 v84, 1.0
	s_and_b64 vcc, exec, s[6:7]
	v_mov_b32_e32 v85, 1.0
	s_cbranch_vccnz .LBB0_343
	global_load_dword v85, v[12:13], off offset:192 nt
.LBB0_343:
	s_and_b64 vcc, exec, s[6:7]
	s_cbranch_vccnz .LBB0_345
	global_load_dword v84, v[12:13], off offset:200 nt
.LBB0_345:
	v_mov_b32_e32 v86, 1.0
	s_and_b64 vcc, exec, s[6:7]
	v_mov_b32_e32 v87, 1.0
	s_cbranch_vccnz .LBB0_347
	global_load_dword v87, v[12:13], off offset:208 nt
.LBB0_347:
	s_and_b64 vcc, exec, s[6:7]
	s_cbranch_vccnz .LBB0_349
	global_load_dword v86, v[12:13], off offset:216 nt
.LBB0_349:
	v_mov_b32_e32 v88, 1.0
	s_and_b64 vcc, exec, s[6:7]
	v_mov_b32_e32 v89, 1.0
	s_cbranch_vccnz .LBB0_351
	global_load_dword v89, v[12:13], off offset:224 nt
.LBB0_351:
	s_and_b64 vcc, exec, s[6:7]
	s_cbranch_vccnz .LBB0_353
	global_load_dword v88, v[12:13], off offset:232 nt
.LBB0_353:
	v_mov_b32_e32 v90, 1.0
	s_and_b64 vcc, exec, s[6:7]
	v_mov_b32_e32 v91, 1.0
	s_cbranch_vccnz .LBB0_355
	global_load_dword v91, v[12:13], off offset:240 nt
.LBB0_355:
	s_and_b64 vcc, exec, s[6:7]
	s_cbranch_vccnz .LBB0_8
	global_load_dword v90, v[12:13], off offset:248 nt
	s_branch .LBB0_8

.LBB0_361:
	s_ashr_i32 s27, s26, 31
	s_add_i32 s14, s26, s55
	s_cmp_lt_i32 s14, s59
	s_cselect_b64 s[28:29], -1, 0
	s_and_b64 s[16:17], s[28:29], exec
	s_cselect_b32 s16, s14, s26
	s_ashr_i32 s17, s16, 31
	s_lshl_b64 s[30:31], s[16:17], 12
	s_add_i32 s20, s12, s26
	s_cmp_lt_i32 s20, s59
	s_cselect_b64 s[24:25], -1, 0
	s_and_b64 s[16:17], s[24:25], exec
	s_cselect_b32 s16, s20, s26
	s_ashr_i32 s17, s16, 31
	s_lshl_b64 s[36:37], s[16:17], 12
	s_add_i32 s16, s60, s26
	s_cmp_lt_i32 s16, s59
	s_cselect_b64 s[22:23], -1, 0
	s_and_b64 s[38:39], s[22:23], exec
	s_cselect_b32 s38, s16, s26
	s_lshl_b64 s[40:41], s[26:27], 12
	s_waitcnt vmcnt(4)
	v_lshl_add_u64 v[2:3], v[50:51], 0, s[40:41]
	s_waitcnt lgkmcnt(0)
	global_load_dwordx4 v[64:67], v[2:3], off nt
	global_load_dwordx4 v[68:71], v[2:3], off offset:1024 nt
	global_load_dwordx4 v[72:75], v[2:3], off offset:2048 nt
	global_load_dwordx4 v[76:79], v[2:3], off offset:3072 nt
	v_lshl_add_u64 v[2:3], v[50:51], 0, s[30:31]
	s_ashr_i32 s39, s38, 31
	global_load_dwordx4 v[46:49], v[2:3], off nt
	global_load_dwordx4 v[42:45], v[2:3], off offset:1024 nt
	global_load_dwordx4 v[38:41], v[2:3], off offset:2048 nt
	global_load_dwordx4 v[34:37], v[2:3], off offset:3072 nt
	v_lshl_add_u64 v[2:3], v[50:51], 0, s[36:37]
	s_lshl_b64 s[30:31], s[38:39], 12
	global_load_dwordx4 v[30:33], v[2:3], off nt
	global_load_dwordx4 v[26:29], v[2:3], off offset:1024 nt
	global_load_dwordx4 v[22:25], v[2:3], off offset:2048 nt
	global_load_dwordx4 v[18:21], v[2:3], off offset:3072 nt
	v_lshl_add_u64 v[2:3], v[50:51], 0, s[30:31]
	global_load_dwordx4 v[14:17], v[2:3], off nt
	global_load_dwordx4 v[10:13], v[2:3], off offset:1024 nt
	global_load_dwordx4 v[6:9], v[2:3], off offset:2048 nt
	s_nop 0
	global_load_dwordx4 v[2:5], v[2:3], off offset:3072 nt
	s_lshl_b64 s[30:31], s[26:27], 11
	s_waitcnt vmcnt(15)
	v_mul_f32_e32 v80, v65, v65
	v_mul_f32_e32 v81, v67, v67
	s_waitcnt vmcnt(14)
	v_mul_f32_e32 v82, v69, v69
	v_mul_f32_e32 v83, v71, v71
	s_waitcnt vmcnt(13)
	v_mul_f32_e32 v84, v73, v73
	v_mul_f32_e32 v85, v75, v75
	v_fmac_f32_e32 v80, v64, v64
	v_fmac_f32_e32 v81, v66, v66
	v_fmac_f32_e32 v82, v68, v68
	v_fmac_f32_e32 v83, v70, v70
	s_waitcnt vmcnt(12)
	v_mul_f32_e32 v86, v77, v77
	v_mul_f32_e32 v87, v79, v79
	v_fmac_f32_e32 v84, v72, v72
	v_fmac_f32_e32 v85, v74, v74
	v_add_f32_e32 v80, v80, v81
	v_add_f32_e32 v81, v82, v83
	v_fmac_f32_e32 v86, v76, v76
	v_fmac_f32_e32 v87, v78, v78
	v_add_f32_e32 v82, v84, v85
	v_add_f32_e32 v80, v81, v80
	v_add_f32_e32 v83, v86, v87
	v_add_f32_e32 v80, v82, v80
	v_add_f32_e32 v80, v83, v80
	ds_bpermute_b32 v81, v58, v80
	v_cvt_pk_bf16_f32 v64, v64, v65
	v_cvt_pk_bf16_f32 v65, v66, v67
	v_cvt_pk_bf16_f32 v66, v68, v69
	v_cvt_pk_bf16_f32 v67, v70, v71
	s_waitcnt lgkmcnt(0)
	v_add_f32_e32 v80, v80, v81
	ds_bpermute_b32 v81, v59, v80
	v_cvt_pk_bf16_f32 v68, v72, v73
	s_waitcnt lgkmcnt(0)
	v_add_f32_e32 v80, v80, v81
	ds_bpermute_b32 v81, v60, v80
	s_waitcnt lgkmcnt(0)
	v_add_f32_e32 v82, v80, v81
	ds_bpermute_b32 v83, v61, v82
	v_lshl_add_u64 v[80:81], v[52:53], 0, s[30:31]
	global_store_dwordx2 v[80:81], v[64:65], off
	global_store_dwordx2 v[80:81], v[66:67], off offset:512
	v_cvt_pk_bf16_f32 v66, v76, v77
	v_cvt_pk_bf16_f32 v67, v78, v79
	s_waitcnt lgkmcnt(0)
	v_add_f32_e32 v69, v82, v83
	ds_bpermute_b32 v82, v62, v69
	global_store_dwordx2 v[80:81], v[66:67], off offset:1536
	s_waitcnt lgkmcnt(0)
	v_add_f32_e32 v64, v69, v82
	ds_bpermute_b32 v65, v63, v64
	v_cvt_pk_bf16_f32 v69, v74, v75
	global_store_dwordx2 v[80:81], v[68:69], off offset:1024
	s_and_saveexec_b64 s[30:31], s[6:7]
	s_cbranch_execz .LBB0_367
	s_waitcnt lgkmcnt(0)
	v_add_f32_e32 v64, v64, v65
	s_lshl_b64 s[26:27], s[26:27], 6
	v_cndmask_b32_e64 v66, 0, v64, s[8:9]
	v_lshl_add_u64 v[64:65], v[54:55], 0, s[26:27]
	global_store_dword v[64:65], v66, off
	s_or_b64 exec, exec, s[30:31]
	s_andn2_b64 vcc, exec, s[28:29]
	s_cbranch_vccz .LBB0_368

.LBB0_377:
	v_ashrrev_i32_e32 v14, 12, v6
	v_lshrrev_b32_e32 v4, 6, v6
	v_ashrrev_i32_e32 v12, 12, v7
	v_lshlrev_b32_e32 v16, 6, v6
	v_ashrrev_i32_e32 v15, 31, v14
	v_lshlrev_b32_e32 v11, 6, v7
	v_and_b32_e32 v17, 63, v4
	v_ashrrev_i32_e32 v13, 31, v12
	v_and_b32_e32 v4, 0xfc0, v16
	v_lshlrev_b64 v[14:15], 14, v[14:15]
	v_and_b32_e32 v11, 0xfc0, v11
	v_lshlrev_b64 v[12:13], 14, v[12:13]
	v_lshlrev_b32_e32 v4, 2, v4
	s_waitcnt lgkmcnt(0)
	v_lshl_add_u64 v[14:15], s[16:17], 0, v[14:15]
	v_lshrrev_b32_e32 v3, 6, v7
	v_lshl_add_u64 v[12:13], s[16:17], 0, v[12:13]
	v_lshl_add_u64 v[14:15], v[14:15], 0, v[4:5]
	v_lshlrev_b32_e32 v4, 2, v11
	v_and_b32_e32 v3, 63, v3
	v_lshl_add_u64 v[12:13], v[12:13], 0, v[4:5]
	v_lshlrev_b32_e32 v4, 2, v17
	v_lshl_add_u64 v[14:15], v[14:15], 0, v[4:5]
	v_lshlrev_b32_e32 v4, 2, v3
	v_lshl_add_u64 v[12:13], v[12:13], 0, v[4:5]
	global_load_dword v3, v[14:15], off nt
	global_load_dword v4, v[12:13], off nt
	v_add_u32_e32 v10, -2, v10
	v_ashrrev_i32_e32 v15, 31, v6
	v_mov_b32_e32 v14, v6
	v_cmp_eq_u32_e32 vcc, 0, v10
	v_ashrrev_i32_e32 v13, 31, v7
	v_mov_b32_e32 v12, v7
	v_add_u32_e32 v7, s9, v7
	v_add_u32_e32 v6, s2, v6
	v_lshl_add_u64 v[14:15], v[14:15], 1, s[20:21]
	s_or_b64 s[22:23], vcc, s[22:23]
	v_lshl_add_u64 v[12:13], v[12:13], 1, s[20:21]
	s_waitcnt vmcnt(0)
	v_cvt_pk_bf16_f32 v3, v3, v4
	global_store_short v[14:15], v3, off
	global_store_short_d16_hi v[12:13], v3, off
	s_andn2_b64 exec, exec, s[22:23]
	s_cbranch_execnz .LBB0_377
	s_or_b64 exec, exec, s[22:23]
	v_cmp_ne_u32_e32 vcc, v8, v9
	v_mad_u64_u32 v[4:5], s[12:13], v9, s8, v[2:3]
	s_orn2_b64 s[20:21], vcc, exec

.LBB0_381:
	v_ashrrev_i32_e32 v10, 12, v4
	v_ashrrev_i32_e32 v11, 31, v10
	v_and_b32_e32 v5, 0xfc0, v3
	v_lshlrev_b64 v[10:11], 14, v[10:11]
	v_lshrrev_b32_e32 v12, 4, v4
	v_lshlrev_b32_e32 v8, 2, v5
	s_waitcnt lgkmcnt(0)
	v_lshl_add_u64 v[10:11], s[16:17], 0, v[10:11]
	v_lshl_add_u64 v[10:11], v[10:11], 0, v[8:9]
	v_and_b32_e32 v8, 0xfc, v12
	v_lshl_add_u64 v[10:11], v[10:11], 0, v[8:9]
	global_load_dword v5, v[10:11], off nt
	v_add_u32_e32 v4, s8, v4
	v_cmp_lt_i32_e32 vcc, s9, v4
	v_add_u32_e32 v3, s2, v3
	s_or_b64 s[20:21], vcc, s[20:21]
	s_waitcnt vmcnt(0)
	v_cvt_pk_bf16_f32 v5, v5, s0
	global_store_short v[6:7], v5, off
	v_lshl_add_u64 v[6:7], v[6:7], 0, s[6:7]
	s_andn2_b64 exec, exec, s[20:21]
	s_cbranch_execnz .LBB0_381

.LBB0_386:
	s_or_b64 exec, exec, s[22:23]
	v_ashrrev_i32_e32 v10, 3, v2
	v_ashrrev_i32_e32 v11, 31, v10
	v_lshl_add_u64 v[12:13], v[10:11], 2, s[18:19]
	global_load_dword v9, v[12:13], off nt
	v_add_u32_e32 v2, s8, v2
	v_cmp_lt_i32_e32 vcc, s2, v2
	s_or_b64 s[12:13], vcc, s[12:13]
	v_lshlrev_b64 v[10:11], 6, v[10:11]
	v_lshl_add_u64 v[10:11], v[4:5], 0, v[10:11]
	s_waitcnt vmcnt(0)
	v_cvt_f32_i32_e32 v9, v9
	v_mul_f32_e32 v8, v8, v9
	v_cvt_f64_f32_e32 v[8:9], v8
	v_mul_f64 v[12:13], v[8:9], s[14:15]
	v_rndne_f64_e32 v[12:13], v[12:13]
	v_fmac_f64_e32 v[8:9], s[16:17], v[12:13]
	v_cvt_i32_f64_e32 v14, v[12:13]
	v_fmac_f64_e32 v[8:9], s[20:21], v[12:13]
	v_and_b32_e32 v12, 3, v14
	v_cvt_f32_f64_e32 v8, v[8:9]
	v_add_u32_e32 v9, -1, v12
	v_mul_f32_e32 v12, v8, v8
	v_fmamk_f32 v16, v12, 0x3638ef1d, v6
	v_fmamk_f32 v17, v12, 0xb493f27e, v7
	v_fmaak_f32 v16, v12, v16, 0x3c088888
	v_fmaak_f32 v17, v12, v17, 0xbab60b61
	v_mul_f32_e32 v15, v12, v8
	v_fmaak_f32 v16, v12, v16, 0xbe2aaaab
	v_fmaak_f32 v17, v12, v17, 0x3d2aaaab
	v_and_b32_e32 v13, 1, v14
	v_fmac_f32_e32 v8, v15, v16
	v_fma_f32 v15, v12, v17, -0.5
	v_and_b32_e32 v14, 2, v14
	v_fma_f32 v12, v12, v15, 1.0
	v_cmp_eq_u32_e32 vcc, 0, v13
	s_nop 1
	v_cndmask_b32_e32 v13, v12, v8, vcc
	v_cndmask_b32_e32 v8, v8, v12, vcc
	v_cmp_eq_u32_e32 vcc, 0, v14
	s_nop 1
	v_cndmask_b32_e64 v12, -v13, v13, vcc
	v_cmp_gt_u32_e32 vcc, 2, v9
	s_nop 1
	v_cndmask_b32_e64 v8, v8, -v8, vcc
	global_store_dword v[10:11], v8, off
	global_store_dword v[10:11], v12, off offset:32
	s_andn2_b64 exec, exec, s[12:13]
	s_cbranch_execz .LBB0_403
